# previous version + scanner inner loops unrolled 8 steps with one lgkmcnt wait per step (R=4 and R=2 copies)
# baseline (speedup 1.0000x reference)
; #define LAS __attribute__((address_space(3)))
; template <int CTRL> __device__ __forceinline__ float dpp_f(float v) { return __builtin_bit_cast(float, __builtin_amdgcn_update_dpp(0, __builtin_bit_cast(int, v), CTRL, 0xF, 0xF, true)); }
; template <int R>
; __device__ __forceinline__ void scan_item(const Args& a, int layer, int q, int rowhalf, LAS unsigned char* lds, int tid, int lane, int wave) {
;     ...
;             for (int s = 0; s < SC_CH; ++s) {
;                 const LAS f32x4* on = op + (s + 1) * 96;
;                 const f32x4 na0 = on[2 * ci], na1 = on[2 * ci + 1], nw0 = on[16 + 2 * ci], nw1 = on[17 + 2 * ci], nb0 = on[32 + 2 * ci], nb1 = on[33 + 2 * ci];
;                 const f32x4 nk0 = on[48 + 2 * ci], nk1 = on[49 + 2 * ci], nr0 = on[64 + 2 * ci], nr1 = on[65 + 2 * ci]; const vecR nv4 = *(const LAS vecR*)((const LAS float*)on + 320 + vrow);
;                 const f32x2 av[4] = {{a0.x, a0.y}, {a0.z, a0.w}, {a1.x, a1.y}, {a1.z, a1.w}}, wv[4] = {{w0.x, w0.y}, {w0.z, w0.w}, {w1.x, w1.y}, {w1.z, w1.w}};
;                 const f32x2 bv[4] = {{b0.x, b0.y}, {b0.z, b0.w}, {b1.x, b1.y}, {b1.z, b1.w}}, kv[4] = {{k0.x, k0.y}, {k0.z, k0.w}, {k1.x, k1.y}, {k1.z, k1.w}};
;                 const f32x2 rv[4] = {{r0.x, r0.y}, {r0.z, r0.w}, {r1.x, r1.y}, {r1.z, r1.w}};
;                 float sa[RL];
; #pragma unroll
;                 for (int i = 0; i < RL; ++i) { f32x2 p = S[i][0] * av[0]; p = S[i][1] * av[1] + p; p = S[i][2] * av[2] + p; p = S[i][3] * av[3] + p;
;                     float t = p.x + p.y; t += dpp_f<0xB1>(t); t += dpp_f<0x4E>(t); t += dpp_f<0x141>(t); sa[i] = t; }
;                 vecR y;
; #pragma unroll
;                 for (int i = 0; i < RL; ++i) { const f32x2 sa2 = {sa[i], sa[i]}, v2 = {v4[i], v4[i]};
; #pragma unroll
;                     for (int c2 = 0; c2 < 4; ++c2) S[i][c2] = S[i][c2] * wv[c2] + sa2 * bv[c2] + v2 * kv[c2];
;                     f32x2 p = S[i][0] * rv[0]; p = S[i][1] * rv[1] + p; p = S[i][2] * rv[2] + p; p = S[i][3] * rv[3] + p;
;                     float t = p.x + p.y; t += dpp_f<0xB1>(t); t += dpp_f<0x4E>(t); t += dpp_f<0x141>(t); y[i] = t; }
;                 if (ci == 0) *(LAS vecR*)(yb + s * (32 * RL) + yrow) = y;
;                 a0 = na0; a1 = na1; w0 = nw0; w1 = nw1; b0 = nb0; b1 = nb1; k0 = nk0; k1 = nk1; r0 = nr0; r1 = nr1; v4 = nv4;
;             }
.Lscnp_loop:
	s_waitcnt lgkmcnt(9)
	v_pk_mul_f32 v[82:83], v[82:83], v[8:9] op_sel_hi:[1,0]
	v_pk_mul_f32 v[84:85], v[84:85], v[8:9] op_sel:[0,1]
	v_pk_mul_f32 v[86:87], v[86:87], v[10:11] op_sel_hi:[1,0]
	v_pk_mul_f32 v[88:89], v[88:89], v[10:11] op_sel:[0,1]
	v_pk_mul_f32 v[90:91], v[90:91], v[12:13] op_sel_hi:[1,0]
	v_pk_mul_f32 v[92:93], v[92:93], v[12:13] op_sel:[0,1]
	v_pk_mul_f32 v[94:95], v[94:95], v[14:15] op_sel_hi:[1,0]
	v_pk_mul_f32 v[96:97], v[96:97], v[14:15] op_sel:[0,1]
	v_pk_fma_f32 v[82:83], v[40:41], v[24:25], v[82:83] op_sel_hi:[1,0,1]
	v_pk_fma_f32 v[84:85], v[40:41], v[24:25], v[84:85] op_sel:[0,1,0]
	v_pk_fma_f32 v[86:87], v[40:41], v[26:27], v[86:87] op_sel_hi:[1,0,1]
	v_pk_fma_f32 v[88:89], v[40:41], v[26:27], v[88:89] op_sel:[0,1,0]
	v_pk_fma_f32 v[90:91], v[40:41], v[28:29], v[90:91] op_sel_hi:[1,0,1]
	v_pk_fma_f32 v[92:93], v[40:41], v[28:29], v[92:93] op_sel:[0,1,0]
	v_pk_fma_f32 v[94:95], v[40:41], v[30:31], v[94:95] op_sel_hi:[1,0,1]
	v_pk_fma_f32 v[96:97], v[40:41], v[30:31], v[96:97] op_sel:[0,1,0]
	v_pk_fma_f32 v[82:83], v[108:109], v[16:17], v[82:83] op_sel_hi:[1,0,1]
	v_pk_fma_f32 v[84:85], v[108:109], v[16:17], v[84:85] op_sel:[0,1,0]
	v_pk_fma_f32 v[86:87], v[108:109], v[18:19], v[86:87] op_sel_hi:[1,0,1]
	v_pk_fma_f32 v[88:89], v[108:109], v[18:19], v[88:89] op_sel:[0,1,0]
	v_pk_fma_f32 v[90:91], v[108:109], v[20:21], v[90:91] op_sel_hi:[1,0,1]
	v_pk_fma_f32 v[92:93], v[108:109], v[20:21], v[92:93] op_sel:[0,1,0]
	v_pk_fma_f32 v[94:95], v[108:109], v[22:23], v[94:95] op_sel_hi:[1,0,1]
	v_pk_fma_f32 v[96:97], v[108:109], v[22:23], v[96:97] op_sel:[0,1,0]
	v_pk_mul_f32 v[108:109], v[82:83], v[42:43] op_sel_hi:[1,0]
	v_pk_mul_f32 v[110:111], v[82:83], v[32:33] op_sel_hi:[1,0]
	v_pk_fma_f32 v[108:109], v[84:85], v[42:43], v[108:109] op_sel:[0,1,0]
	v_pk_fma_f32 v[110:111], v[84:85], v[32:33], v[110:111] op_sel:[0,1,0]
	v_pk_fma_f32 v[108:109], v[86:87], v[44:45], v[108:109] op_sel_hi:[1,0,1]
	v_pk_fma_f32 v[110:111], v[86:87], v[34:35], v[110:111] op_sel_hi:[1,0,1]
	v_pk_fma_f32 v[108:109], v[88:89], v[44:45], v[108:109] op_sel:[0,1,0]
	v_pk_fma_f32 v[110:111], v[88:89], v[34:35], v[110:111] op_sel:[0,1,0]
	v_pk_fma_f32 v[108:109], v[90:91], v[46:47], v[108:109] op_sel_hi:[1,0,1]
	v_pk_fma_f32 v[110:111], v[90:91], v[36:37], v[110:111] op_sel_hi:[1,0,1]
	v_pk_fma_f32 v[108:109], v[92:93], v[46:47], v[108:109] op_sel:[0,1,0]
	v_pk_fma_f32 v[110:111], v[92:93], v[36:37], v[110:111] op_sel:[0,1,0]
	v_pk_fma_f32 v[108:109], v[94:95], v[48:49], v[108:109] op_sel_hi:[1,0,1]
	v_pk_fma_f32 v[110:111], v[94:95], v[38:39], v[110:111] op_sel_hi:[1,0,1]
	v_pk_fma_f32 v[108:109], v[96:97], v[48:49], v[108:109] op_sel:[0,1,0]
	v_pk_fma_f32 v[110:111], v[96:97], v[38:39], v[110:111] op_sel:[0,1,0]
	ds_read_b128 v[0:3], v107 offset:3072
	ds_read_b128 v[4:7], v107 offset:3088
	ds_read_b128 v[8:11], v107 offset:3328
	ds_read_b128 v[12:15], v107 offset:3344
	ds_read_b128 v[24:27], v107 offset:3840
	ds_read_b128 v[28:31], v107 offset:3856
	ds_read_b64 v[40:41], v106 offset:4352
	ds_read_b128 v[16:19], v107 offset:3584
	ds_read_b128 v[20:23], v107 offset:3600
	ds_read_b128 v[32:35], v107 offset:4096
	ds_read_b128 v[36:39], v107 offset:4112
	v_add_f32_dpp v108, v108, v108 quad_perm:[1,0,3,2] row_mask:0xf bank_mask:0xf bound_ctrl:1
	v_add_f32_dpp v109, v109, v109 quad_perm:[1,0,3,2] row_mask:0xf bank_mask:0xf bound_ctrl:1
	v_add_f32_dpp v110, v110, v110 quad_perm:[1,0,3,2] row_mask:0xf bank_mask:0xf bound_ctrl:1
	v_add_f32_dpp v111, v111, v111 quad_perm:[1,0,3,2] row_mask:0xf bank_mask:0xf bound_ctrl:1
	v_add_f32_dpp v108, v108, v108 quad_perm:[2,3,0,1] row_mask:0xf bank_mask:0xf bound_ctrl:1
	v_add_f32_dpp v109, v109, v109 quad_perm:[2,3,0,1] row_mask:0xf bank_mask:0xf bound_ctrl:1
	v_add_f32_dpp v110, v110, v110 quad_perm:[2,3,0,1] row_mask:0xf bank_mask:0xf bound_ctrl:1
	v_add_f32_dpp v111, v111, v111 quad_perm:[2,3,0,1] row_mask:0xf bank_mask:0xf bound_ctrl:1
	v_add_f32_dpp v108, v108, v108 row_half_mirror row_mask:0xf bank_mask:0xf bound_ctrl:1
	v_add_f32_dpp v109, v109, v109 row_half_mirror row_mask:0xf bank_mask:0xf bound_ctrl:1
	v_add_f32_dpp v110, v110, v110 row_half_mirror row_mask:0xf bank_mask:0xf bound_ctrl:1
	v_add_f32_dpp v111, v111, v111 row_half_mirror row_mask:0xf bank_mask:0xf bound_ctrl:1
	ds_write_b64 v105, v[110:111] offset:0
	s_waitcnt lgkmcnt(9)
; #define LAS __attribute__((address_space(3)))
; template <int CTRL> __device__ __forceinline__ float dpp_f(float v) { return __builtin_bit_cast(float, __builtin_amdgcn_update_dpp(0, __builtin_bit_cast(int, v), CTRL, 0xF, 0xF, true)); }
; template <int R>
; __device__ __forceinline__ void scan_item(const Args& a, int layer, int q, int rowhalf, LAS unsigned char* lds, int tid, int lane, int wave) {
;     ...
;             for (int s = 0; s < SC_CH; ++s) {
;                 const LAS f32x4* on = op + (s + 1) * 96;
;                 const f32x4 na0 = on[2 * ci], na1 = on[2 * ci + 1], nw0 = on[16 + 2 * ci], nw1 = on[17 + 2 * ci], nb0 = on[32 + 2 * ci], nb1 = on[33 + 2 * ci];
;                 const f32x4 nk0 = on[48 + 2 * ci], nk1 = on[49 + 2 * ci], nr0 = on[64 + 2 * ci], nr1 = on[65 + 2 * ci]; const vecR nv4 = *(const LAS vecR*)((const LAS float*)on + 320 + vrow);
;                 const f32x2 av[4] = {{a0.x, a0.y}, {a0.z, a0.w}, {a1.x, a1.y}, {a1.z, a1.w}}, wv[4] = {{w0.x, w0.y}, {w0.z, w0.w}, {w1.x, w1.y}, {w1.z, w1.w}};
;                 const f32x2 bv[4] = {{b0.x, b0.y}, {b0.z, b0.w}, {b1.x, b1.y}, {b1.z, b1.w}}, kv[4] = {{k0.x, k0.y}, {k0.z, k0.w}, {k1.x, k1.y}, {k1.z, k1.w}};
;                 const f32x2 rv[4] = {{r0.x, r0.y}, {r0.z, r0.w}, {r1.x, r1.y}, {r1.z, r1.w}};
;                 float sa[RL];
; #pragma unroll
;                 for (int i = 0; i < RL; ++i) { f32x2 p = S[i][0] * av[0]; p = S[i][1] * av[1] + p; p = S[i][2] * av[2] + p; p = S[i][3] * av[3] + p;
;                     float t = p.x + p.y; t += dpp_f<0xB1>(t); t += dpp_f<0x4E>(t); t += dpp_f<0x141>(t); sa[i] = t; }
;                 vecR y;
; #pragma unroll
;                 for (int i = 0; i < RL; ++i) { const f32x2 sa2 = {sa[i], sa[i]}, v2 = {v4[i], v4[i]};
; #pragma unroll
;                     for (int c2 = 0; c2 < 4; ++c2) S[i][c2] = S[i][c2] * wv[c2] + sa2 * bv[c2] + v2 * kv[c2];
;                     f32x2 p = S[i][0] * rv[0]; p = S[i][1] * rv[1] + p; p = S[i][2] * rv[2] + p; p = S[i][3] * rv[3] + p;
;                     float t = p.x + p.y; t += dpp_f<0xB1>(t); t += dpp_f<0x4E>(t); t += dpp_f<0x141>(t); y[i] = t; }
;                 if (ci == 0) *(LAS vecR*)(yb + s * (32 * RL) + yrow) = y;
;                 a0 = na0; a1 = na1; w0 = nw0; w1 = nw1; b0 = nb0; b1 = nb1; k0 = nk0; k1 = nk1; r0 = nr0; r1 = nr1; v4 = nv4;
;             }
	v_pk_mul_f32 v[82:83], v[82:83], v[50:51] op_sel_hi:[1,0]
	v_pk_mul_f32 v[84:85], v[84:85], v[50:51] op_sel:[0,1]
	v_pk_mul_f32 v[86:87], v[86:87], v[52:53] op_sel_hi:[1,0]
	v_pk_mul_f32 v[88:89], v[88:89], v[52:53] op_sel:[0,1]
	v_pk_mul_f32 v[90:91], v[90:91], v[54:55] op_sel_hi:[1,0]
	v_pk_mul_f32 v[92:93], v[92:93], v[54:55] op_sel:[0,1]
	v_pk_mul_f32 v[94:95], v[94:95], v[56:57] op_sel_hi:[1,0]
	v_pk_mul_f32 v[96:97], v[96:97], v[56:57] op_sel:[0,1]
	v_pk_fma_f32 v[82:83], v[98:99], v[66:67], v[82:83] op_sel_hi:[1,0,1]
	v_pk_fma_f32 v[84:85], v[98:99], v[66:67], v[84:85] op_sel:[0,1,0]
	v_pk_fma_f32 v[86:87], v[98:99], v[68:69], v[86:87] op_sel_hi:[1,0,1]
	v_pk_fma_f32 v[88:89], v[98:99], v[68:69], v[88:89] op_sel:[0,1,0]
	v_pk_fma_f32 v[90:91], v[98:99], v[70:71], v[90:91] op_sel_hi:[1,0,1]
	v_pk_fma_f32 v[92:93], v[98:99], v[70:71], v[92:93] op_sel:[0,1,0]
	v_pk_fma_f32 v[94:95], v[98:99], v[72:73], v[94:95] op_sel_hi:[1,0,1]
	v_pk_fma_f32 v[96:97], v[98:99], v[72:73], v[96:97] op_sel:[0,1,0]
	v_pk_fma_f32 v[82:83], v[108:109], v[58:59], v[82:83] op_sel_hi:[1,0,1]
	v_pk_fma_f32 v[84:85], v[108:109], v[58:59], v[84:85] op_sel:[0,1,0]
	v_pk_fma_f32 v[86:87], v[108:109], v[60:61], v[86:87] op_sel_hi:[1,0,1]
	v_pk_fma_f32 v[88:89], v[108:109], v[60:61], v[88:89] op_sel:[0,1,0]
	v_pk_fma_f32 v[90:91], v[108:109], v[62:63], v[90:91] op_sel_hi:[1,0,1]
	v_pk_fma_f32 v[92:93], v[108:109], v[62:63], v[92:93] op_sel:[0,1,0]
	v_pk_fma_f32 v[94:95], v[108:109], v[64:65], v[94:95] op_sel_hi:[1,0,1]
	v_pk_fma_f32 v[96:97], v[108:109], v[64:65], v[96:97] op_sel:[0,1,0]
	v_pk_mul_f32 v[108:109], v[82:83], v[0:1] op_sel_hi:[1,0]
	v_pk_mul_f32 v[110:111], v[82:83], v[74:75] op_sel_hi:[1,0]
	v_pk_fma_f32 v[108:109], v[84:85], v[0:1], v[108:109] op_sel:[0,1,0]
	v_pk_fma_f32 v[110:111], v[84:85], v[74:75], v[110:111] op_sel:[0,1,0]
	v_pk_fma_f32 v[108:109], v[86:87], v[2:3], v[108:109] op_sel_hi:[1,0,1]
	v_pk_fma_f32 v[110:111], v[86:87], v[76:77], v[110:111] op_sel_hi:[1,0,1]
	v_pk_fma_f32 v[108:109], v[88:89], v[2:3], v[108:109] op_sel:[0,1,0]
	v_pk_fma_f32 v[110:111], v[88:89], v[76:77], v[110:111] op_sel:[0,1,0]
	v_pk_fma_f32 v[108:109], v[90:91], v[4:5], v[108:109] op_sel_hi:[1,0,1]
	v_pk_fma_f32 v[110:111], v[90:91], v[78:79], v[110:111] op_sel_hi:[1,0,1]
	v_pk_fma_f32 v[108:109], v[92:93], v[4:5], v[108:109] op_sel:[0,1,0]
	v_pk_fma_f32 v[110:111], v[92:93], v[78:79], v[110:111] op_sel:[0,1,0]
	v_pk_fma_f32 v[108:109], v[94:95], v[6:7], v[108:109] op_sel_hi:[1,0,1]
	v_pk_fma_f32 v[110:111], v[94:95], v[80:81], v[110:111] op_sel_hi:[1,0,1]
	v_pk_fma_f32 v[108:109], v[96:97], v[6:7], v[108:109] op_sel:[0,1,0]
	v_pk_fma_f32 v[110:111], v[96:97], v[80:81], v[110:111] op_sel:[0,1,0]
	ds_read_b128 v[42:45], v107 offset:4608
	ds_read_b128 v[46:49], v107 offset:4624
	ds_read_b128 v[50:53], v107 offset:4864
	ds_read_b128 v[54:57], v107 offset:4880
	ds_read_b128 v[66:69], v107 offset:5376
	ds_read_b128 v[70:73], v107 offset:5392
	ds_read_b64 v[98:99], v106 offset:5888
	ds_read_b128 v[58:61], v107 offset:5120
	ds_read_b128 v[62:65], v107 offset:5136
	ds_read_b128 v[74:77], v107 offset:5632
	ds_read_b128 v[78:81], v107 offset:5648
	v_add_f32_dpp v108, v108, v108 quad_perm:[1,0,3,2] row_mask:0xf bank_mask:0xf bound_ctrl:1
	v_add_f32_dpp v109, v109, v109 quad_perm:[1,0,3,2] row_mask:0xf bank_mask:0xf bound_ctrl:1
	v_add_f32_dpp v110, v110, v110 quad_perm:[1,0,3,2] row_mask:0xf bank_mask:0xf bound_ctrl:1
	v_add_f32_dpp v111, v111, v111 quad_perm:[1,0,3,2] row_mask:0xf bank_mask:0xf bound_ctrl:1
	v_add_f32_dpp v108, v108, v108 quad_perm:[2,3,0,1] row_mask:0xf bank_mask:0xf bound_ctrl:1
	v_add_f32_dpp v109, v109, v109 quad_perm:[2,3,0,1] row_mask:0xf bank_mask:0xf bound_ctrl:1
	v_add_f32_dpp v110, v110, v110 quad_perm:[2,3,0,1] row_mask:0xf bank_mask:0xf bound_ctrl:1
	v_add_f32_dpp v111, v111, v111 quad_perm:[2,3,0,1] row_mask:0xf bank_mask:0xf bound_ctrl:1
	v_add_f32_dpp v108, v108, v108 row_half_mirror row_mask:0xf bank_mask:0xf bound_ctrl:1
	v_add_f32_dpp v109, v109, v109 row_half_mirror row_mask:0xf bank_mask:0xf bound_ctrl:1
	v_add_f32_dpp v110, v110, v110 row_half_mirror row_mask:0xf bank_mask:0xf bound_ctrl:1
	v_add_f32_dpp v111, v111, v111 row_half_mirror row_mask:0xf bank_mask:0xf bound_ctrl:1
	ds_write_b64 v105, v[110:111] offset:256
	s_waitcnt lgkmcnt(9)
; #define LAS __attribute__((address_space(3)))
; template <int CTRL> __device__ __forceinline__ float dpp_f(float v) { return __builtin_bit_cast(float, __builtin_amdgcn_update_dpp(0, __builtin_bit_cast(int, v), CTRL, 0xF, 0xF, true)); }
; template <int R>
; __device__ __forceinline__ void scan_item(const Args& a, int layer, int q, int rowhalf, LAS unsigned char* lds, int tid, int lane, int wave) {
;     ...
;             for (int s = 0; s < SC_CH; ++s) {
;                 const LAS f32x4* on = op + (s + 1) * 96;
;                 const f32x4 na0 = on[2 * ci], na1 = on[2 * ci + 1], nw0 = on[16 + 2 * ci], nw1 = on[17 + 2 * ci], nb0 = on[32 + 2 * ci], nb1 = on[33 + 2 * ci];
;                 const f32x4 nk0 = on[48 + 2 * ci], nk1 = on[49 + 2 * ci], nr0 = on[64 + 2 * ci], nr1 = on[65 + 2 * ci]; const vecR nv4 = *(const LAS vecR*)((const LAS float*)on + 320 + vrow);
;                 const f32x2 av[4] = {{a0.x, a0.y}, {a0.z, a0.w}, {a1.x, a1.y}, {a1.z, a1.w}}, wv[4] = {{w0.x, w0.y}, {w0.z, w0.w}, {w1.x, w1.y}, {w1.z, w1.w}};
;                 const f32x2 bv[4] = {{b0.x, b0.y}, {b0.z, b0.w}, {b1.x, b1.y}, {b1.z, b1.w}}, kv[4] = {{k0.x, k0.y}, {k0.z, k0.w}, {k1.x, k1.y}, {k1.z, k1.w}};
;                 const f32x2 rv[4] = {{r0.x, r0.y}, {r0.z, r0.w}, {r1.x, r1.y}, {r1.z, r1.w}};
;                 float sa[RL];
; #pragma unroll
;                 for (int i = 0; i < RL; ++i) { f32x2 p = S[i][0] * av[0]; p = S[i][1] * av[1] + p; p = S[i][2] * av[2] + p; p = S[i][3] * av[3] + p;
;                     float t = p.x + p.y; t += dpp_f<0xB1>(t); t += dpp_f<0x4E>(t); t += dpp_f<0x141>(t); sa[i] = t; }
;                 vecR y;
; #pragma unroll
;                 for (int i = 0; i < RL; ++i) { const f32x2 sa2 = {sa[i], sa[i]}, v2 = {v4[i], v4[i]};
; #pragma unroll
;                     for (int c2 = 0; c2 < 4; ++c2) S[i][c2] = S[i][c2] * wv[c2] + sa2 * bv[c2] + v2 * kv[c2];
;                     f32x2 p = S[i][0] * rv[0]; p = S[i][1] * rv[1] + p; p = S[i][2] * rv[2] + p; p = S[i][3] * rv[3] + p;
;                     float t = p.x + p.y; t += dpp_f<0xB1>(t); t += dpp_f<0x4E>(t); t += dpp_f<0x141>(t); y[i] = t; }
;                 if (ci == 0) *(LAS vecR*)(yb + s * (32 * RL) + yrow) = y;
;                 a0 = na0; a1 = na1; w0 = nw0; w1 = nw1; b0 = nb0; b1 = nb1; k0 = nk0; k1 = nk1; r0 = nr0; r1 = nr1; v4 = nv4;
;             }
	v_pk_mul_f32 v[82:83], v[82:83], v[8:9] op_sel_hi:[1,0]
	v_pk_mul_f32 v[84:85], v[84:85], v[8:9] op_sel:[0,1]
	v_pk_mul_f32 v[86:87], v[86:87], v[10:11] op_sel_hi:[1,0]
	v_pk_mul_f32 v[88:89], v[88:89], v[10:11] op_sel:[0,1]
	v_pk_mul_f32 v[90:91], v[90:91], v[12:13] op_sel_hi:[1,0]
	v_pk_mul_f32 v[92:93], v[92:93], v[12:13] op_sel:[0,1]
	v_pk_mul_f32 v[94:95], v[94:95], v[14:15] op_sel_hi:[1,0]
	v_pk_mul_f32 v[96:97], v[96:97], v[14:15] op_sel:[0,1]
	v_pk_fma_f32 v[82:83], v[40:41], v[24:25], v[82:83] op_sel_hi:[1,0,1]
	v_pk_fma_f32 v[84:85], v[40:41], v[24:25], v[84:85] op_sel:[0,1,0]
	v_pk_fma_f32 v[86:87], v[40:41], v[26:27], v[86:87] op_sel_hi:[1,0,1]
	v_pk_fma_f32 v[88:89], v[40:41], v[26:27], v[88:89] op_sel:[0,1,0]
	v_pk_fma_f32 v[90:91], v[40:41], v[28:29], v[90:91] op_sel_hi:[1,0,1]
	v_pk_fma_f32 v[92:93], v[40:41], v[28:29], v[92:93] op_sel:[0,1,0]
	v_pk_fma_f32 v[94:95], v[40:41], v[30:31], v[94:95] op_sel_hi:[1,0,1]
	v_pk_fma_f32 v[96:97], v[40:41], v[30:31], v[96:97] op_sel:[0,1,0]
	v_pk_fma_f32 v[82:83], v[108:109], v[16:17], v[82:83] op_sel_hi:[1,0,1]
	v_pk_fma_f32 v[84:85], v[108:109], v[16:17], v[84:85] op_sel:[0,1,0]
	v_pk_fma_f32 v[86:87], v[108:109], v[18:19], v[86:87] op_sel_hi:[1,0,1]
	v_pk_fma_f32 v[88:89], v[108:109], v[18:19], v[88:89] op_sel:[0,1,0]
	v_pk_fma_f32 v[90:91], v[108:109], v[20:21], v[90:91] op_sel_hi:[1,0,1]
	v_pk_fma_f32 v[92:93], v[108:109], v[20:21], v[92:93] op_sel:[0,1,0]
	v_pk_fma_f32 v[94:95], v[108:109], v[22:23], v[94:95] op_sel_hi:[1,0,1]
	v_pk_fma_f32 v[96:97], v[108:109], v[22:23], v[96:97] op_sel:[0,1,0]
	v_pk_mul_f32 v[108:109], v[82:83], v[42:43] op_sel_hi:[1,0]
	v_pk_mul_f32 v[110:111], v[82:83], v[32:33] op_sel_hi:[1,0]
	v_pk_fma_f32 v[108:109], v[84:85], v[42:43], v[108:109] op_sel:[0,1,0]
	v_pk_fma_f32 v[110:111], v[84:85], v[32:33], v[110:111] op_sel:[0,1,0]
	v_pk_fma_f32 v[108:109], v[86:87], v[44:45], v[108:109] op_sel_hi:[1,0,1]
	v_pk_fma_f32 v[110:111], v[86:87], v[34:35], v[110:111] op_sel_hi:[1,0,1]
	v_pk_fma_f32 v[108:109], v[88:89], v[44:45], v[108:109] op_sel:[0,1,0]
	v_pk_fma_f32 v[110:111], v[88:89], v[34:35], v[110:111] op_sel:[0,1,0]
	v_pk_fma_f32 v[108:109], v[90:91], v[46:47], v[108:109] op_sel_hi:[1,0,1]
	v_pk_fma_f32 v[110:111], v[90:91], v[36:37], v[110:111] op_sel_hi:[1,0,1]
	v_pk_fma_f32 v[108:109], v[92:93], v[46:47], v[108:109] op_sel:[0,1,0]
	v_pk_fma_f32 v[110:111], v[92:93], v[36:37], v[110:111] op_sel:[0,1,0]
	v_pk_fma_f32 v[108:109], v[94:95], v[48:49], v[108:109] op_sel_hi:[1,0,1]
	v_pk_fma_f32 v[110:111], v[94:95], v[38:39], v[110:111] op_sel_hi:[1,0,1]
	v_pk_fma_f32 v[108:109], v[96:97], v[48:49], v[108:109] op_sel:[0,1,0]
	v_pk_fma_f32 v[110:111], v[96:97], v[38:39], v[110:111] op_sel:[0,1,0]
	ds_read_b128 v[0:3], v107 offset:6144
	ds_read_b128 v[4:7], v107 offset:6160
	ds_read_b128 v[8:11], v107 offset:6400
	ds_read_b128 v[12:15], v107 offset:6416
	ds_read_b128 v[24:27], v107 offset:6912
	ds_read_b128 v[28:31], v107 offset:6928
	ds_read_b64 v[40:41], v106 offset:7424
	ds_read_b128 v[16:19], v107 offset:6656
	ds_read_b128 v[20:23], v107 offset:6672
	ds_read_b128 v[32:35], v107 offset:7168
	ds_read_b128 v[36:39], v107 offset:7184
	v_add_f32_dpp v108, v108, v108 quad_perm:[1,0,3,2] row_mask:0xf bank_mask:0xf bound_ctrl:1
	v_add_f32_dpp v109, v109, v109 quad_perm:[1,0,3,2] row_mask:0xf bank_mask:0xf bound_ctrl:1
	v_add_f32_dpp v110, v110, v110 quad_perm:[1,0,3,2] row_mask:0xf bank_mask:0xf bound_ctrl:1
	v_add_f32_dpp v111, v111, v111 quad_perm:[1,0,3,2] row_mask:0xf bank_mask:0xf bound_ctrl:1
	v_add_f32_dpp v108, v108, v108 quad_perm:[2,3,0,1] row_mask:0xf bank_mask:0xf bound_ctrl:1
	v_add_f32_dpp v109, v109, v109 quad_perm:[2,3,0,1] row_mask:0xf bank_mask:0xf bound_ctrl:1
	v_add_f32_dpp v110, v110, v110 quad_perm:[2,3,0,1] row_mask:0xf bank_mask:0xf bound_ctrl:1
	v_add_f32_dpp v111, v111, v111 quad_perm:[2,3,0,1] row_mask:0xf bank_mask:0xf bound_ctrl:1
	v_add_f32_dpp v108, v108, v108 row_half_mirror row_mask:0xf bank_mask:0xf bound_ctrl:1
	v_add_f32_dpp v109, v109, v109 row_half_mirror row_mask:0xf bank_mask:0xf bound_ctrl:1
	v_add_f32_dpp v110, v110, v110 row_half_mirror row_mask:0xf bank_mask:0xf bound_ctrl:1
	v_add_f32_dpp v111, v111, v111 row_half_mirror row_mask:0xf bank_mask:0xf bound_ctrl:1
	ds_write_b64 v105, v[110:111] offset:512
	s_waitcnt lgkmcnt(9)
; #define LAS __attribute__((address_space(3)))
; template <int CTRL> __device__ __forceinline__ float dpp_f(float v) { return __builtin_bit_cast(float, __builtin_amdgcn_update_dpp(0, __builtin_bit_cast(int, v), CTRL, 0xF, 0xF, true)); }
; template <int R>
; __device__ __forceinline__ void scan_item(const Args& a, int layer, int q, int rowhalf, LAS unsigned char* lds, int tid, int lane, int wave) {
;     ...
;             for (int s = 0; s < SC_CH; ++s) {
;                 const LAS f32x4* on = op + (s + 1) * 96;
;                 const f32x4 na0 = on[2 * ci], na1 = on[2 * ci + 1], nw0 = on[16 + 2 * ci], nw1 = on[17 + 2 * ci], nb0 = on[32 + 2 * ci], nb1 = on[33 + 2 * ci];
;                 const f32x4 nk0 = on[48 + 2 * ci], nk1 = on[49 + 2 * ci], nr0 = on[64 + 2 * ci], nr1 = on[65 + 2 * ci]; const vecR nv4 = *(const LAS vecR*)((const LAS float*)on + 320 + vrow);
;                 const f32x2 av[4] = {{a0.x, a0.y}, {a0.z, a0.w}, {a1.x, a1.y}, {a1.z, a1.w}}, wv[4] = {{w0.x, w0.y}, {w0.z, w0.w}, {w1.x, w1.y}, {w1.z, w1.w}};
;                 const f32x2 bv[4] = {{b0.x, b0.y}, {b0.z, b0.w}, {b1.x, b1.y}, {b1.z, b1.w}}, kv[4] = {{k0.x, k0.y}, {k0.z, k0.w}, {k1.x, k1.y}, {k1.z, k1.w}};
;                 const f32x2 rv[4] = {{r0.x, r0.y}, {r0.z, r0.w}, {r1.x, r1.y}, {r1.z, r1.w}};
;                 float sa[RL];
; #pragma unroll
;                 for (int i = 0; i < RL; ++i) { f32x2 p = S[i][0] * av[0]; p = S[i][1] * av[1] + p; p = S[i][2] * av[2] + p; p = S[i][3] * av[3] + p;
;                     float t = p.x + p.y; t += dpp_f<0xB1>(t); t += dpp_f<0x4E>(t); t += dpp_f<0x141>(t); sa[i] = t; }
;                 vecR y;
; #pragma unroll
;                 for (int i = 0; i < RL; ++i) { const f32x2 sa2 = {sa[i], sa[i]}, v2 = {v4[i], v4[i]};
; #pragma unroll
;                     for (int c2 = 0; c2 < 4; ++c2) S[i][c2] = S[i][c2] * wv[c2] + sa2 * bv[c2] + v2 * kv[c2];
;                     f32x2 p = S[i][0] * rv[0]; p = S[i][1] * rv[1] + p; p = S[i][2] * rv[2] + p; p = S[i][3] * rv[3] + p;
;                     float t = p.x + p.y; t += dpp_f<0xB1>(t); t += dpp_f<0x4E>(t); t += dpp_f<0x141>(t); y[i] = t; }
;                 if (ci == 0) *(LAS vecR*)(yb + s * (32 * RL) + yrow) = y;
;                 a0 = na0; a1 = na1; w0 = nw0; w1 = nw1; b0 = nb0; b1 = nb1; k0 = nk0; k1 = nk1; r0 = nr0; r1 = nr1; v4 = nv4;
;             }
	v_pk_mul_f32 v[82:83], v[82:83], v[50:51] op_sel_hi:[1,0]
	v_pk_mul_f32 v[84:85], v[84:85], v[50:51] op_sel:[0,1]
	v_pk_mul_f32 v[86:87], v[86:87], v[52:53] op_sel_hi:[1,0]
	v_pk_mul_f32 v[88:89], v[88:89], v[52:53] op_sel:[0,1]
	v_pk_mul_f32 v[90:91], v[90:91], v[54:55] op_sel_hi:[1,0]
	v_pk_mul_f32 v[92:93], v[92:93], v[54:55] op_sel:[0,1]
	v_pk_mul_f32 v[94:95], v[94:95], v[56:57] op_sel_hi:[1,0]
	v_pk_mul_f32 v[96:97], v[96:97], v[56:57] op_sel:[0,1]
	v_pk_fma_f32 v[82:83], v[98:99], v[66:67], v[82:83] op_sel_hi:[1,0,1]
	v_pk_fma_f32 v[84:85], v[98:99], v[66:67], v[84:85] op_sel:[0,1,0]
	v_pk_fma_f32 v[86:87], v[98:99], v[68:69], v[86:87] op_sel_hi:[1,0,1]
	v_pk_fma_f32 v[88:89], v[98:99], v[68:69], v[88:89] op_sel:[0,1,0]
	v_pk_fma_f32 v[90:91], v[98:99], v[70:71], v[90:91] op_sel_hi:[1,0,1]
	v_pk_fma_f32 v[92:93], v[98:99], v[70:71], v[92:93] op_sel:[0,1,0]
	v_pk_fma_f32 v[94:95], v[98:99], v[72:73], v[94:95] op_sel_hi:[1,0,1]
	v_pk_fma_f32 v[96:97], v[98:99], v[72:73], v[96:97] op_sel:[0,1,0]
	v_pk_fma_f32 v[82:83], v[108:109], v[58:59], v[82:83] op_sel_hi:[1,0,1]
	v_pk_fma_f32 v[84:85], v[108:109], v[58:59], v[84:85] op_sel:[0,1,0]
	v_pk_fma_f32 v[86:87], v[108:109], v[60:61], v[86:87] op_sel_hi:[1,0,1]
	v_pk_fma_f32 v[88:89], v[108:109], v[60:61], v[88:89] op_sel:[0,1,0]
	v_pk_fma_f32 v[90:91], v[108:109], v[62:63], v[90:91] op_sel_hi:[1,0,1]
	v_pk_fma_f32 v[92:93], v[108:109], v[62:63], v[92:93] op_sel:[0,1,0]
	v_pk_fma_f32 v[94:95], v[108:109], v[64:65], v[94:95] op_sel_hi:[1,0,1]
	v_pk_fma_f32 v[96:97], v[108:109], v[64:65], v[96:97] op_sel:[0,1,0]
	v_pk_mul_f32 v[108:109], v[82:83], v[0:1] op_sel_hi:[1,0]
	v_pk_mul_f32 v[110:111], v[82:83], v[74:75] op_sel_hi:[1,0]
	v_pk_fma_f32 v[108:109], v[84:85], v[0:1], v[108:109] op_sel:[0,1,0]
	v_pk_fma_f32 v[110:111], v[84:85], v[74:75], v[110:111] op_sel:[0,1,0]
	v_pk_fma_f32 v[108:109], v[86:87], v[2:3], v[108:109] op_sel_hi:[1,0,1]
	v_pk_fma_f32 v[110:111], v[86:87], v[76:77], v[110:111] op_sel_hi:[1,0,1]
	v_pk_fma_f32 v[108:109], v[88:89], v[2:3], v[108:109] op_sel:[0,1,0]
	v_pk_fma_f32 v[110:111], v[88:89], v[76:77], v[110:111] op_sel:[0,1,0]
	v_pk_fma_f32 v[108:109], v[90:91], v[4:5], v[108:109] op_sel_hi:[1,0,1]
	v_pk_fma_f32 v[110:111], v[90:91], v[78:79], v[110:111] op_sel_hi:[1,0,1]
	v_pk_fma_f32 v[108:109], v[92:93], v[4:5], v[108:109] op_sel:[0,1,0]
	v_pk_fma_f32 v[110:111], v[92:93], v[78:79], v[110:111] op_sel:[0,1,0]
	v_pk_fma_f32 v[108:109], v[94:95], v[6:7], v[108:109] op_sel_hi:[1,0,1]
	v_pk_fma_f32 v[110:111], v[94:95], v[80:81], v[110:111] op_sel_hi:[1,0,1]
	v_pk_fma_f32 v[108:109], v[96:97], v[6:7], v[108:109] op_sel:[0,1,0]
	v_pk_fma_f32 v[110:111], v[96:97], v[80:81], v[110:111] op_sel:[0,1,0]
	ds_read_b128 v[42:45], v107 offset:7680
	ds_read_b128 v[46:49], v107 offset:7696
	ds_read_b128 v[50:53], v107 offset:7936
	ds_read_b128 v[54:57], v107 offset:7952
	ds_read_b128 v[66:69], v107 offset:8448
	ds_read_b128 v[70:73], v107 offset:8464
	ds_read_b64 v[98:99], v106 offset:8960
	ds_read_b128 v[58:61], v107 offset:8192
	ds_read_b128 v[62:65], v107 offset:8208
	ds_read_b128 v[74:77], v107 offset:8704
	ds_read_b128 v[78:81], v107 offset:8720
	v_add_f32_dpp v108, v108, v108 quad_perm:[1,0,3,2] row_mask:0xf bank_mask:0xf bound_ctrl:1
	v_add_f32_dpp v109, v109, v109 quad_perm:[1,0,3,2] row_mask:0xf bank_mask:0xf bound_ctrl:1
	v_add_f32_dpp v110, v110, v110 quad_perm:[1,0,3,2] row_mask:0xf bank_mask:0xf bound_ctrl:1
	v_add_f32_dpp v111, v111, v111 quad_perm:[1,0,3,2] row_mask:0xf bank_mask:0xf bound_ctrl:1
	v_add_f32_dpp v108, v108, v108 quad_perm:[2,3,0,1] row_mask:0xf bank_mask:0xf bound_ctrl:1
	v_add_f32_dpp v109, v109, v109 quad_perm:[2,3,0,1] row_mask:0xf bank_mask:0xf bound_ctrl:1
	v_add_f32_dpp v110, v110, v110 quad_perm:[2,3,0,1] row_mask:0xf bank_mask:0xf bound_ctrl:1
	v_add_f32_dpp v111, v111, v111 quad_perm:[2,3,0,1] row_mask:0xf bank_mask:0xf bound_ctrl:1
	v_add_f32_dpp v108, v108, v108 row_half_mirror row_mask:0xf bank_mask:0xf bound_ctrl:1
	v_add_f32_dpp v109, v109, v109 row_half_mirror row_mask:0xf bank_mask:0xf bound_ctrl:1
	v_add_f32_dpp v110, v110, v110 row_half_mirror row_mask:0xf bank_mask:0xf bound_ctrl:1
	v_add_f32_dpp v111, v111, v111 row_half_mirror row_mask:0xf bank_mask:0xf bound_ctrl:1
	ds_write_b64 v105, v[110:111] offset:768
	s_waitcnt lgkmcnt(9)
; #define LAS __attribute__((address_space(3)))
; template <int CTRL> __device__ __forceinline__ float dpp_f(float v) { return __builtin_bit_cast(float, __builtin_amdgcn_update_dpp(0, __builtin_bit_cast(int, v), CTRL, 0xF, 0xF, true)); }
; template <int R>
; __device__ __forceinline__ void scan_item(const Args& a, int layer, int q, int rowhalf, LAS unsigned char* lds, int tid, int lane, int wave) {
;     ...
;             for (int s = 0; s < SC_CH; ++s) {
;                 const LAS f32x4* on = op + (s + 1) * 96;
;                 const f32x4 na0 = on[2 * ci], na1 = on[2 * ci + 1], nw0 = on[16 + 2 * ci], nw1 = on[17 + 2 * ci], nb0 = on[32 + 2 * ci], nb1 = on[33 + 2 * ci];
;                 const f32x4 nk0 = on[48 + 2 * ci], nk1 = on[49 + 2 * ci], nr0 = on[64 + 2 * ci], nr1 = on[65 + 2 * ci]; const vecR nv4 = *(const LAS vecR*)((const LAS float*)on + 320 + vrow);
;                 const f32x2 av[4] = {{a0.x, a0.y}, {a0.z, a0.w}, {a1.x, a1.y}, {a1.z, a1.w}}, wv[4] = {{w0.x, w0.y}, {w0.z, w0.w}, {w1.x, w1.y}, {w1.z, w1.w}};
;                 const f32x2 bv[4] = {{b0.x, b0.y}, {b0.z, b0.w}, {b1.x, b1.y}, {b1.z, b1.w}}, kv[4] = {{k0.x, k0.y}, {k0.z, k0.w}, {k1.x, k1.y}, {k1.z, k1.w}};
;                 const f32x2 rv[4] = {{r0.x, r0.y}, {r0.z, r0.w}, {r1.x, r1.y}, {r1.z, r1.w}};
;                 float sa[RL];
; #pragma unroll
;                 for (int i = 0; i < RL; ++i) { f32x2 p = S[i][0] * av[0]; p = S[i][1] * av[1] + p; p = S[i][2] * av[2] + p; p = S[i][3] * av[3] + p;
;                     float t = p.x + p.y; t += dpp_f<0xB1>(t); t += dpp_f<0x4E>(t); t += dpp_f<0x141>(t); sa[i] = t; }
;                 vecR y;
; #pragma unroll
;                 for (int i = 0; i < RL; ++i) { const f32x2 sa2 = {sa[i], sa[i]}, v2 = {v4[i], v4[i]};
; #pragma unroll
;                     for (int c2 = 0; c2 < 4; ++c2) S[i][c2] = S[i][c2] * wv[c2] + sa2 * bv[c2] + v2 * kv[c2];
;                     f32x2 p = S[i][0] * rv[0]; p = S[i][1] * rv[1] + p; p = S[i][2] * rv[2] + p; p = S[i][3] * rv[3] + p;
;                     float t = p.x + p.y; t += dpp_f<0xB1>(t); t += dpp_f<0x4E>(t); t += dpp_f<0x141>(t); y[i] = t; }
;                 if (ci == 0) *(LAS vecR*)(yb + s * (32 * RL) + yrow) = y;
;                 a0 = na0; a1 = na1; w0 = nw0; w1 = nw1; b0 = nb0; b1 = nb1; k0 = nk0; k1 = nk1; r0 = nr0; r1 = nr1; v4 = nv4;
;             }
	v_pk_mul_f32 v[82:83], v[82:83], v[8:9] op_sel_hi:[1,0]
	v_pk_mul_f32 v[84:85], v[84:85], v[8:9] op_sel:[0,1]
	v_pk_mul_f32 v[86:87], v[86:87], v[10:11] op_sel_hi:[1,0]
	v_pk_mul_f32 v[88:89], v[88:89], v[10:11] op_sel:[0,1]
	v_pk_mul_f32 v[90:91], v[90:91], v[12:13] op_sel_hi:[1,0]
	v_pk_mul_f32 v[92:93], v[92:93], v[12:13] op_sel:[0,1]
	v_pk_mul_f32 v[94:95], v[94:95], v[14:15] op_sel_hi:[1,0]
	v_pk_mul_f32 v[96:97], v[96:97], v[14:15] op_sel:[0,1]
	v_pk_fma_f32 v[82:83], v[40:41], v[24:25], v[82:83] op_sel_hi:[1,0,1]
	v_pk_fma_f32 v[84:85], v[40:41], v[24:25], v[84:85] op_sel:[0,1,0]
	v_pk_fma_f32 v[86:87], v[40:41], v[26:27], v[86:87] op_sel_hi:[1,0,1]
	v_pk_fma_f32 v[88:89], v[40:41], v[26:27], v[88:89] op_sel:[0,1,0]
	v_pk_fma_f32 v[90:91], v[40:41], v[28:29], v[90:91] op_sel_hi:[1,0,1]
	v_pk_fma_f32 v[92:93], v[40:41], v[28:29], v[92:93] op_sel:[0,1,0]
	v_pk_fma_f32 v[94:95], v[40:41], v[30:31], v[94:95] op_sel_hi:[1,0,1]
	v_pk_fma_f32 v[96:97], v[40:41], v[30:31], v[96:97] op_sel:[0,1,0]
	v_pk_fma_f32 v[82:83], v[108:109], v[16:17], v[82:83] op_sel_hi:[1,0,1]
	v_pk_fma_f32 v[84:85], v[108:109], v[16:17], v[84:85] op_sel:[0,1,0]
	v_pk_fma_f32 v[86:87], v[108:109], v[18:19], v[86:87] op_sel_hi:[1,0,1]
	v_pk_fma_f32 v[88:89], v[108:109], v[18:19], v[88:89] op_sel:[0,1,0]
	v_pk_fma_f32 v[90:91], v[108:109], v[20:21], v[90:91] op_sel_hi:[1,0,1]
	v_pk_fma_f32 v[92:93], v[108:109], v[20:21], v[92:93] op_sel:[0,1,0]
	v_pk_fma_f32 v[94:95], v[108:109], v[22:23], v[94:95] op_sel_hi:[1,0,1]
	v_pk_fma_f32 v[96:97], v[108:109], v[22:23], v[96:97] op_sel:[0,1,0]
	v_pk_mul_f32 v[108:109], v[82:83], v[42:43] op_sel_hi:[1,0]
	v_pk_mul_f32 v[110:111], v[82:83], v[32:33] op_sel_hi:[1,0]
	v_pk_fma_f32 v[108:109], v[84:85], v[42:43], v[108:109] op_sel:[0,1,0]
	v_pk_fma_f32 v[110:111], v[84:85], v[32:33], v[110:111] op_sel:[0,1,0]
	v_pk_fma_f32 v[108:109], v[86:87], v[44:45], v[108:109] op_sel_hi:[1,0,1]
	v_pk_fma_f32 v[110:111], v[86:87], v[34:35], v[110:111] op_sel_hi:[1,0,1]
	v_pk_fma_f32 v[108:109], v[88:89], v[44:45], v[108:109] op_sel:[0,1,0]
	v_pk_fma_f32 v[110:111], v[88:89], v[34:35], v[110:111] op_sel:[0,1,0]
	v_pk_fma_f32 v[108:109], v[90:91], v[46:47], v[108:109] op_sel_hi:[1,0,1]
	v_pk_fma_f32 v[110:111], v[90:91], v[36:37], v[110:111] op_sel_hi:[1,0,1]
	v_pk_fma_f32 v[108:109], v[92:93], v[46:47], v[108:109] op_sel:[0,1,0]
	v_pk_fma_f32 v[110:111], v[92:93], v[36:37], v[110:111] op_sel:[0,1,0]
	v_pk_fma_f32 v[108:109], v[94:95], v[48:49], v[108:109] op_sel_hi:[1,0,1]
	v_pk_fma_f32 v[110:111], v[94:95], v[38:39], v[110:111] op_sel_hi:[1,0,1]
	v_pk_fma_f32 v[108:109], v[96:97], v[48:49], v[108:109] op_sel:[0,1,0]
	v_pk_fma_f32 v[110:111], v[96:97], v[38:39], v[110:111] op_sel:[0,1,0]
	ds_read_b128 v[0:3], v107 offset:9216
	ds_read_b128 v[4:7], v107 offset:9232
	ds_read_b128 v[8:11], v107 offset:9472
	ds_read_b128 v[12:15], v107 offset:9488
	ds_read_b128 v[24:27], v107 offset:9984
	ds_read_b128 v[28:31], v107 offset:10000
	ds_read_b64 v[40:41], v106 offset:10496
	ds_read_b128 v[16:19], v107 offset:9728
	ds_read_b128 v[20:23], v107 offset:9744
	ds_read_b128 v[32:35], v107 offset:10240
	ds_read_b128 v[36:39], v107 offset:10256
	v_add_f32_dpp v108, v108, v108 quad_perm:[1,0,3,2] row_mask:0xf bank_mask:0xf bound_ctrl:1
	v_add_f32_dpp v109, v109, v109 quad_perm:[1,0,3,2] row_mask:0xf bank_mask:0xf bound_ctrl:1
	v_add_f32_dpp v110, v110, v110 quad_perm:[1,0,3,2] row_mask:0xf bank_mask:0xf bound_ctrl:1
	v_add_f32_dpp v111, v111, v111 quad_perm:[1,0,3,2] row_mask:0xf bank_mask:0xf bound_ctrl:1
	v_add_f32_dpp v108, v108, v108 quad_perm:[2,3,0,1] row_mask:0xf bank_mask:0xf bound_ctrl:1
	v_add_f32_dpp v109, v109, v109 quad_perm:[2,3,0,1] row_mask:0xf bank_mask:0xf bound_ctrl:1
	v_add_f32_dpp v110, v110, v110 quad_perm:[2,3,0,1] row_mask:0xf bank_mask:0xf bound_ctrl:1
	v_add_f32_dpp v111, v111, v111 quad_perm:[2,3,0,1] row_mask:0xf bank_mask:0xf bound_ctrl:1
	v_add_f32_dpp v108, v108, v108 row_half_mirror row_mask:0xf bank_mask:0xf bound_ctrl:1
	v_add_f32_dpp v109, v109, v109 row_half_mirror row_mask:0xf bank_mask:0xf bound_ctrl:1
	v_add_f32_dpp v110, v110, v110 row_half_mirror row_mask:0xf bank_mask:0xf bound_ctrl:1
	v_add_f32_dpp v111, v111, v111 row_half_mirror row_mask:0xf bank_mask:0xf bound_ctrl:1
	ds_write_b64 v105, v[110:111] offset:1024
	s_waitcnt lgkmcnt(9)
; #define LAS __attribute__((address_space(3)))
; template <int CTRL> __device__ __forceinline__ float dpp_f(float v) { return __builtin_bit_cast(float, __builtin_amdgcn_update_dpp(0, __builtin_bit_cast(int, v), CTRL, 0xF, 0xF, true)); }
; template <int R>
; __device__ __forceinline__ void scan_item(const Args& a, int layer, int q, int rowhalf, LAS unsigned char* lds, int tid, int lane, int wave) {
;     ...
;             for (int s = 0; s < SC_CH; ++s) {
;                 const LAS f32x4* on = op + (s + 1) * 96;
;                 const f32x4 na0 = on[2 * ci], na1 = on[2 * ci + 1], nw0 = on[16 + 2 * ci], nw1 = on[17 + 2 * ci], nb0 = on[32 + 2 * ci], nb1 = on[33 + 2 * ci];
;                 const f32x4 nk0 = on[48 + 2 * ci], nk1 = on[49 + 2 * ci], nr0 = on[64 + 2 * ci], nr1 = on[65 + 2 * ci]; const vecR nv4 = *(const LAS vecR*)((const LAS float*)on + 320 + vrow);
;                 const f32x2 av[4] = {{a0.x, a0.y}, {a0.z, a0.w}, {a1.x, a1.y}, {a1.z, a1.w}}, wv[4] = {{w0.x, w0.y}, {w0.z, w0.w}, {w1.x, w1.y}, {w1.z, w1.w}};
;                 const f32x2 bv[4] = {{b0.x, b0.y}, {b0.z, b0.w}, {b1.x, b1.y}, {b1.z, b1.w}}, kv[4] = {{k0.x, k0.y}, {k0.z, k0.w}, {k1.x, k1.y}, {k1.z, k1.w}};
;                 const f32x2 rv[4] = {{r0.x, r0.y}, {r0.z, r0.w}, {r1.x, r1.y}, {r1.z, r1.w}};
;                 float sa[RL];
; #pragma unroll
;                 for (int i = 0; i < RL; ++i) { f32x2 p = S[i][0] * av[0]; p = S[i][1] * av[1] + p; p = S[i][2] * av[2] + p; p = S[i][3] * av[3] + p;
;                     float t = p.x + p.y; t += dpp_f<0xB1>(t); t += dpp_f<0x4E>(t); t += dpp_f<0x141>(t); sa[i] = t; }
;                 vecR y;
; #pragma unroll
;                 for (int i = 0; i < RL; ++i) { const f32x2 sa2 = {sa[i], sa[i]}, v2 = {v4[i], v4[i]};
; #pragma unroll
;                     for (int c2 = 0; c2 < 4; ++c2) S[i][c2] = S[i][c2] * wv[c2] + sa2 * bv[c2] + v2 * kv[c2];
;                     f32x2 p = S[i][0] * rv[0]; p = S[i][1] * rv[1] + p; p = S[i][2] * rv[2] + p; p = S[i][3] * rv[3] + p;
;                     float t = p.x + p.y; t += dpp_f<0xB1>(t); t += dpp_f<0x4E>(t); t += dpp_f<0x141>(t); y[i] = t; }
;                 if (ci == 0) *(LAS vecR*)(yb + s * (32 * RL) + yrow) = y;
;                 a0 = na0; a1 = na1; w0 = nw0; w1 = nw1; b0 = nb0; b1 = nb1; k0 = nk0; k1 = nk1; r0 = nr0; r1 = nr1; v4 = nv4;
;             }
	v_pk_mul_f32 v[82:83], v[82:83], v[50:51] op_sel_hi:[1,0]
	v_pk_mul_f32 v[84:85], v[84:85], v[50:51] op_sel:[0,1]
	v_pk_mul_f32 v[86:87], v[86:87], v[52:53] op_sel_hi:[1,0]
	v_pk_mul_f32 v[88:89], v[88:89], v[52:53] op_sel:[0,1]
	v_pk_mul_f32 v[90:91], v[90:91], v[54:55] op_sel_hi:[1,0]
	v_pk_mul_f32 v[92:93], v[92:93], v[54:55] op_sel:[0,1]
	v_pk_mul_f32 v[94:95], v[94:95], v[56:57] op_sel_hi:[1,0]
	v_pk_mul_f32 v[96:97], v[96:97], v[56:57] op_sel:[0,1]
	v_pk_fma_f32 v[82:83], v[98:99], v[66:67], v[82:83] op_sel_hi:[1,0,1]
	v_pk_fma_f32 v[84:85], v[98:99], v[66:67], v[84:85] op_sel:[0,1,0]
	v_pk_fma_f32 v[86:87], v[98:99], v[68:69], v[86:87] op_sel_hi:[1,0,1]
	v_pk_fma_f32 v[88:89], v[98:99], v[68:69], v[88:89] op_sel:[0,1,0]
	v_pk_fma_f32 v[90:91], v[98:99], v[70:71], v[90:91] op_sel_hi:[1,0,1]
	v_pk_fma_f32 v[92:93], v[98:99], v[70:71], v[92:93] op_sel:[0,1,0]
	v_pk_fma_f32 v[94:95], v[98:99], v[72:73], v[94:95] op_sel_hi:[1,0,1]
	v_pk_fma_f32 v[96:97], v[98:99], v[72:73], v[96:97] op_sel:[0,1,0]
	v_pk_fma_f32 v[82:83], v[108:109], v[58:59], v[82:83] op_sel_hi:[1,0,1]
	v_pk_fma_f32 v[84:85], v[108:109], v[58:59], v[84:85] op_sel:[0,1,0]
	v_pk_fma_f32 v[86:87], v[108:109], v[60:61], v[86:87] op_sel_hi:[1,0,1]
	v_pk_fma_f32 v[88:89], v[108:109], v[60:61], v[88:89] op_sel:[0,1,0]
	v_pk_fma_f32 v[90:91], v[108:109], v[62:63], v[90:91] op_sel_hi:[1,0,1]
	v_pk_fma_f32 v[92:93], v[108:109], v[62:63], v[92:93] op_sel:[0,1,0]
	v_pk_fma_f32 v[94:95], v[108:109], v[64:65], v[94:95] op_sel_hi:[1,0,1]
	v_pk_fma_f32 v[96:97], v[108:109], v[64:65], v[96:97] op_sel:[0,1,0]
	v_pk_mul_f32 v[108:109], v[82:83], v[0:1] op_sel_hi:[1,0]
	v_pk_mul_f32 v[110:111], v[82:83], v[74:75] op_sel_hi:[1,0]
	v_pk_fma_f32 v[108:109], v[84:85], v[0:1], v[108:109] op_sel:[0,1,0]
	v_pk_fma_f32 v[110:111], v[84:85], v[74:75], v[110:111] op_sel:[0,1,0]
	v_pk_fma_f32 v[108:109], v[86:87], v[2:3], v[108:109] op_sel_hi:[1,0,1]
	v_pk_fma_f32 v[110:111], v[86:87], v[76:77], v[110:111] op_sel_hi:[1,0,1]
	v_pk_fma_f32 v[108:109], v[88:89], v[2:3], v[108:109] op_sel:[0,1,0]
	v_pk_fma_f32 v[110:111], v[88:89], v[76:77], v[110:111] op_sel:[0,1,0]
	v_pk_fma_f32 v[108:109], v[90:91], v[4:5], v[108:109] op_sel_hi:[1,0,1]
	v_pk_fma_f32 v[110:111], v[90:91], v[78:79], v[110:111] op_sel_hi:[1,0,1]
	v_pk_fma_f32 v[108:109], v[92:93], v[4:5], v[108:109] op_sel:[0,1,0]
	v_pk_fma_f32 v[110:111], v[92:93], v[78:79], v[110:111] op_sel:[0,1,0]
	v_pk_fma_f32 v[108:109], v[94:95], v[6:7], v[108:109] op_sel_hi:[1,0,1]
	v_pk_fma_f32 v[110:111], v[94:95], v[80:81], v[110:111] op_sel_hi:[1,0,1]
	v_pk_fma_f32 v[108:109], v[96:97], v[6:7], v[108:109] op_sel:[0,1,0]
	v_pk_fma_f32 v[110:111], v[96:97], v[80:81], v[110:111] op_sel:[0,1,0]
	ds_read_b128 v[42:45], v107 offset:10752
	ds_read_b128 v[46:49], v107 offset:10768
	ds_read_b128 v[50:53], v107 offset:11008
	ds_read_b128 v[54:57], v107 offset:11024
	ds_read_b128 v[66:69], v107 offset:11520
	ds_read_b128 v[70:73], v107 offset:11536
	ds_read_b64 v[98:99], v106 offset:12032
	ds_read_b128 v[58:61], v107 offset:11264
	ds_read_b128 v[62:65], v107 offset:11280
	ds_read_b128 v[74:77], v107 offset:11776
	ds_read_b128 v[78:81], v107 offset:11792
	v_add_f32_dpp v108, v108, v108 quad_perm:[1,0,3,2] row_mask:0xf bank_mask:0xf bound_ctrl:1
	v_add_f32_dpp v109, v109, v109 quad_perm:[1,0,3,2] row_mask:0xf bank_mask:0xf bound_ctrl:1
	v_add_f32_dpp v110, v110, v110 quad_perm:[1,0,3,2] row_mask:0xf bank_mask:0xf bound_ctrl:1
	v_add_f32_dpp v111, v111, v111 quad_perm:[1,0,3,2] row_mask:0xf bank_mask:0xf bound_ctrl:1
	v_add_f32_dpp v108, v108, v108 quad_perm:[2,3,0,1] row_mask:0xf bank_mask:0xf bound_ctrl:1
	v_add_f32_dpp v109, v109, v109 quad_perm:[2,3,0,1] row_mask:0xf bank_mask:0xf bound_ctrl:1
	v_add_f32_dpp v110, v110, v110 quad_perm:[2,3,0,1] row_mask:0xf bank_mask:0xf bound_ctrl:1
	v_add_f32_dpp v111, v111, v111 quad_perm:[2,3,0,1] row_mask:0xf bank_mask:0xf bound_ctrl:1
	v_add_f32_dpp v108, v108, v108 row_half_mirror row_mask:0xf bank_mask:0xf bound_ctrl:1
	v_add_f32_dpp v109, v109, v109 row_half_mirror row_mask:0xf bank_mask:0xf bound_ctrl:1
	v_add_f32_dpp v110, v110, v110 row_half_mirror row_mask:0xf bank_mask:0xf bound_ctrl:1
	v_add_f32_dpp v111, v111, v111 row_half_mirror row_mask:0xf bank_mask:0xf bound_ctrl:1
	ds_write_b64 v105, v[110:111] offset:1280
	s_waitcnt lgkmcnt(9)
; #define LAS __attribute__((address_space(3)))
; template <int CTRL> __device__ __forceinline__ float dpp_f(float v) { return __builtin_bit_cast(float, __builtin_amdgcn_update_dpp(0, __builtin_bit_cast(int, v), CTRL, 0xF, 0xF, true)); }
; template <int R>
; __device__ __forceinline__ void scan_item(const Args& a, int layer, int q, int rowhalf, LAS unsigned char* lds, int tid, int lane, int wave) {
;     ...
;             for (int s = 0; s < SC_CH; ++s) {
;                 const LAS f32x4* on = op + (s + 1) * 96;
;                 const f32x4 na0 = on[2 * ci], na1 = on[2 * ci + 1], nw0 = on[16 + 2 * ci], nw1 = on[17 + 2 * ci], nb0 = on[32 + 2 * ci], nb1 = on[33 + 2 * ci];
;                 const f32x4 nk0 = on[48 + 2 * ci], nk1 = on[49 + 2 * ci], nr0 = on[64 + 2 * ci], nr1 = on[65 + 2 * ci]; const vecR nv4 = *(const LAS vecR*)((const LAS float*)on + 320 + vrow);
;                 const f32x2 av[4] = {{a0.x, a0.y}, {a0.z, a0.w}, {a1.x, a1.y}, {a1.z, a1.w}}, wv[4] = {{w0.x, w0.y}, {w0.z, w0.w}, {w1.x, w1.y}, {w1.z, w1.w}};
;                 const f32x2 bv[4] = {{b0.x, b0.y}, {b0.z, b0.w}, {b1.x, b1.y}, {b1.z, b1.w}}, kv[4] = {{k0.x, k0.y}, {k0.z, k0.w}, {k1.x, k1.y}, {k1.z, k1.w}};
;                 const f32x2 rv[4] = {{r0.x, r0.y}, {r0.z, r0.w}, {r1.x, r1.y}, {r1.z, r1.w}};
;                 float sa[RL];
; #pragma unroll
;                 for (int i = 0; i < RL; ++i) { f32x2 p = S[i][0] * av[0]; p = S[i][1] * av[1] + p; p = S[i][2] * av[2] + p; p = S[i][3] * av[3] + p;
;                     float t = p.x + p.y; t += dpp_f<0xB1>(t); t += dpp_f<0x4E>(t); t += dpp_f<0x141>(t); sa[i] = t; }
;                 vecR y;
; #pragma unroll
;                 for (int i = 0; i < RL; ++i) { const f32x2 sa2 = {sa[i], sa[i]}, v2 = {v4[i], v4[i]};
; #pragma unroll
;                     for (int c2 = 0; c2 < 4; ++c2) S[i][c2] = S[i][c2] * wv[c2] + sa2 * bv[c2] + v2 * kv[c2];
;                     f32x2 p = S[i][0] * rv[0]; p = S[i][1] * rv[1] + p; p = S[i][2] * rv[2] + p; p = S[i][3] * rv[3] + p;
;                     float t = p.x + p.y; t += dpp_f<0xB1>(t); t += dpp_f<0x4E>(t); t += dpp_f<0x141>(t); y[i] = t; }
;                 if (ci == 0) *(LAS vecR*)(yb + s * (32 * RL) + yrow) = y;
;                 a0 = na0; a1 = na1; w0 = nw0; w1 = nw1; b0 = nb0; b1 = nb1; k0 = nk0; k1 = nk1; r0 = nr0; r1 = nr1; v4 = nv4;
;             }
	v_pk_mul_f32 v[82:83], v[82:83], v[8:9] op_sel_hi:[1,0]
	v_pk_mul_f32 v[84:85], v[84:85], v[8:9] op_sel:[0,1]
	v_pk_mul_f32 v[86:87], v[86:87], v[10:11] op_sel_hi:[1,0]
	v_pk_mul_f32 v[88:89], v[88:89], v[10:11] op_sel:[0,1]
	v_pk_mul_f32 v[90:91], v[90:91], v[12:13] op_sel_hi:[1,0]
	v_pk_mul_f32 v[92:93], v[92:93], v[12:13] op_sel:[0,1]
	v_pk_mul_f32 v[94:95], v[94:95], v[14:15] op_sel_hi:[1,0]
	v_pk_mul_f32 v[96:97], v[96:97], v[14:15] op_sel:[0,1]
	v_pk_fma_f32 v[82:83], v[40:41], v[24:25], v[82:83] op_sel_hi:[1,0,1]
	v_pk_fma_f32 v[84:85], v[40:41], v[24:25], v[84:85] op_sel:[0,1,0]
	v_pk_fma_f32 v[86:87], v[40:41], v[26:27], v[86:87] op_sel_hi:[1,0,1]
	v_pk_fma_f32 v[88:89], v[40:41], v[26:27], v[88:89] op_sel:[0,1,0]
	v_pk_fma_f32 v[90:91], v[40:41], v[28:29], v[90:91] op_sel_hi:[1,0,1]
	v_pk_fma_f32 v[92:93], v[40:41], v[28:29], v[92:93] op_sel:[0,1,0]
	v_pk_fma_f32 v[94:95], v[40:41], v[30:31], v[94:95] op_sel_hi:[1,0,1]
	v_pk_fma_f32 v[96:97], v[40:41], v[30:31], v[96:97] op_sel:[0,1,0]
	v_pk_fma_f32 v[82:83], v[108:109], v[16:17], v[82:83] op_sel_hi:[1,0,1]
	v_pk_fma_f32 v[84:85], v[108:109], v[16:17], v[84:85] op_sel:[0,1,0]
	v_pk_fma_f32 v[86:87], v[108:109], v[18:19], v[86:87] op_sel_hi:[1,0,1]
	v_pk_fma_f32 v[88:89], v[108:109], v[18:19], v[88:89] op_sel:[0,1,0]
	v_pk_fma_f32 v[90:91], v[108:109], v[20:21], v[90:91] op_sel_hi:[1,0,1]
	v_pk_fma_f32 v[92:93], v[108:109], v[20:21], v[92:93] op_sel:[0,1,0]
	v_pk_fma_f32 v[94:95], v[108:109], v[22:23], v[94:95] op_sel_hi:[1,0,1]
	v_pk_fma_f32 v[96:97], v[108:109], v[22:23], v[96:97] op_sel:[0,1,0]
	v_pk_mul_f32 v[108:109], v[82:83], v[42:43] op_sel_hi:[1,0]
	v_pk_mul_f32 v[110:111], v[82:83], v[32:33] op_sel_hi:[1,0]
	v_pk_fma_f32 v[108:109], v[84:85], v[42:43], v[108:109] op_sel:[0,1,0]
	v_pk_fma_f32 v[110:111], v[84:85], v[32:33], v[110:111] op_sel:[0,1,0]
	v_pk_fma_f32 v[108:109], v[86:87], v[44:45], v[108:109] op_sel_hi:[1,0,1]
	v_pk_fma_f32 v[110:111], v[86:87], v[34:35], v[110:111] op_sel_hi:[1,0,1]
	v_pk_fma_f32 v[108:109], v[88:89], v[44:45], v[108:109] op_sel:[0,1,0]
	v_pk_fma_f32 v[110:111], v[88:89], v[34:35], v[110:111] op_sel:[0,1,0]
	v_pk_fma_f32 v[108:109], v[90:91], v[46:47], v[108:109] op_sel_hi:[1,0,1]
	v_pk_fma_f32 v[110:111], v[90:91], v[36:37], v[110:111] op_sel_hi:[1,0,1]
	v_pk_fma_f32 v[108:109], v[92:93], v[46:47], v[108:109] op_sel:[0,1,0]
	v_pk_fma_f32 v[110:111], v[92:93], v[36:37], v[110:111] op_sel:[0,1,0]
	v_pk_fma_f32 v[108:109], v[94:95], v[48:49], v[108:109] op_sel_hi:[1,0,1]
	v_pk_fma_f32 v[110:111], v[94:95], v[38:39], v[110:111] op_sel_hi:[1,0,1]
	v_pk_fma_f32 v[108:109], v[96:97], v[48:49], v[108:109] op_sel:[0,1,0]
	v_pk_fma_f32 v[110:111], v[96:97], v[38:39], v[110:111] op_sel:[0,1,0]
	ds_read_b128 v[0:3], v107 offset:12288
	ds_read_b128 v[4:7], v107 offset:12304
	ds_read_b128 v[8:11], v107 offset:12544
	ds_read_b128 v[12:15], v107 offset:12560
	ds_read_b128 v[24:27], v107 offset:13056
	ds_read_b128 v[28:31], v107 offset:13072
	ds_read_b64 v[40:41], v106 offset:13568
	ds_read_b128 v[16:19], v107 offset:12800
	ds_read_b128 v[20:23], v107 offset:12816
	ds_read_b128 v[32:35], v107 offset:13312
	ds_read_b128 v[36:39], v107 offset:13328
	v_add_f32_dpp v108, v108, v108 quad_perm:[1,0,3,2] row_mask:0xf bank_mask:0xf bound_ctrl:1
	v_add_f32_dpp v109, v109, v109 quad_perm:[1,0,3,2] row_mask:0xf bank_mask:0xf bound_ctrl:1
	v_add_f32_dpp v110, v110, v110 quad_perm:[1,0,3,2] row_mask:0xf bank_mask:0xf bound_ctrl:1
	v_add_f32_dpp v111, v111, v111 quad_perm:[1,0,3,2] row_mask:0xf bank_mask:0xf bound_ctrl:1
	v_add_f32_dpp v108, v108, v108 quad_perm:[2,3,0,1] row_mask:0xf bank_mask:0xf bound_ctrl:1
	v_add_f32_dpp v109, v109, v109 quad_perm:[2,3,0,1] row_mask:0xf bank_mask:0xf bound_ctrl:1
	v_add_f32_dpp v110, v110, v110 quad_perm:[2,3,0,1] row_mask:0xf bank_mask:0xf bound_ctrl:1
	v_add_f32_dpp v111, v111, v111 quad_perm:[2,3,0,1] row_mask:0xf bank_mask:0xf bound_ctrl:1
	v_add_f32_dpp v108, v108, v108 row_half_mirror row_mask:0xf bank_mask:0xf bound_ctrl:1
	v_add_f32_dpp v109, v109, v109 row_half_mirror row_mask:0xf bank_mask:0xf bound_ctrl:1
	v_add_f32_dpp v110, v110, v110 row_half_mirror row_mask:0xf bank_mask:0xf bound_ctrl:1
	v_add_f32_dpp v111, v111, v111 row_half_mirror row_mask:0xf bank_mask:0xf bound_ctrl:1
	ds_write_b64 v105, v[110:111] offset:1536
	s_waitcnt lgkmcnt(9)
; #define LAS __attribute__((address_space(3)))
; template <int CTRL> __device__ __forceinline__ float dpp_f(float v) { return __builtin_bit_cast(float, __builtin_amdgcn_update_dpp(0, __builtin_bit_cast(int, v), CTRL, 0xF, 0xF, true)); }
; template <int R>
; __device__ __forceinline__ void scan_item(const Args& a, int layer, int q, int rowhalf, LAS unsigned char* lds, int tid, int lane, int wave) {
;     ...
;             for (int s = 0; s < SC_CH; ++s) {
;                 const LAS f32x4* on = op + (s + 1) * 96;
;                 const f32x4 na0 = on[2 * ci], na1 = on[2 * ci + 1], nw0 = on[16 + 2 * ci], nw1 = on[17 + 2 * ci], nb0 = on[32 + 2 * ci], nb1 = on[33 + 2 * ci];
;                 const f32x4 nk0 = on[48 + 2 * ci], nk1 = on[49 + 2 * ci], nr0 = on[64 + 2 * ci], nr1 = on[65 + 2 * ci]; const vecR nv4 = *(const LAS vecR*)((const LAS float*)on + 320 + vrow);
;                 const f32x2 av[4] = {{a0.x, a0.y}, {a0.z, a0.w}, {a1.x, a1.y}, {a1.z, a1.w}}, wv[4] = {{w0.x, w0.y}, {w0.z, w0.w}, {w1.x, w1.y}, {w1.z, w1.w}};
;                 const f32x2 bv[4] = {{b0.x, b0.y}, {b0.z, b0.w}, {b1.x, b1.y}, {b1.z, b1.w}}, kv[4] = {{k0.x, k0.y}, {k0.z, k0.w}, {k1.x, k1.y}, {k1.z, k1.w}};
;                 const f32x2 rv[4] = {{r0.x, r0.y}, {r0.z, r0.w}, {r1.x, r1.y}, {r1.z, r1.w}};
;                 float sa[RL];
; #pragma unroll
;                 for (int i = 0; i < RL; ++i) { f32x2 p = S[i][0] * av[0]; p = S[i][1] * av[1] + p; p = S[i][2] * av[2] + p; p = S[i][3] * av[3] + p;
;                     float t = p.x + p.y; t += dpp_f<0xB1>(t); t += dpp_f<0x4E>(t); t += dpp_f<0x141>(t); sa[i] = t; }
;                 vecR y;
; #pragma unroll
;                 for (int i = 0; i < RL; ++i) { const f32x2 sa2 = {sa[i], sa[i]}, v2 = {v4[i], v4[i]};
; #pragma unroll
;                     for (int c2 = 0; c2 < 4; ++c2) S[i][c2] = S[i][c2] * wv[c2] + sa2 * bv[c2] + v2 * kv[c2];
;                     f32x2 p = S[i][0] * rv[0]; p = S[i][1] * rv[1] + p; p = S[i][2] * rv[2] + p; p = S[i][3] * rv[3] + p;
;                     float t = p.x + p.y; t += dpp_f<0xB1>(t); t += dpp_f<0x4E>(t); t += dpp_f<0x141>(t); y[i] = t; }
;                 if (ci == 0) *(LAS vecR*)(yb + s * (32 * RL) + yrow) = y;
;                 a0 = na0; a1 = na1; w0 = nw0; w1 = nw1; b0 = nb0; b1 = nb1; k0 = nk0; k1 = nk1; r0 = nr0; r1 = nr1; v4 = nv4;
;             }
;             __syncthreads();
	v_pk_mul_f32 v[82:83], v[82:83], v[50:51] op_sel_hi:[1,0]
	v_pk_mul_f32 v[84:85], v[84:85], v[50:51] op_sel:[0,1]
	v_pk_mul_f32 v[86:87], v[86:87], v[52:53] op_sel_hi:[1,0]
	v_pk_mul_f32 v[88:89], v[88:89], v[52:53] op_sel:[0,1]
	v_pk_mul_f32 v[90:91], v[90:91], v[54:55] op_sel_hi:[1,0]
	v_pk_mul_f32 v[92:93], v[92:93], v[54:55] op_sel:[0,1]
	v_pk_mul_f32 v[94:95], v[94:95], v[56:57] op_sel_hi:[1,0]
	v_pk_mul_f32 v[96:97], v[96:97], v[56:57] op_sel:[0,1]
	v_pk_fma_f32 v[82:83], v[98:99], v[66:67], v[82:83] op_sel_hi:[1,0,1]
	v_pk_fma_f32 v[84:85], v[98:99], v[66:67], v[84:85] op_sel:[0,1,0]
	v_pk_fma_f32 v[86:87], v[98:99], v[68:69], v[86:87] op_sel_hi:[1,0,1]
	v_pk_fma_f32 v[88:89], v[98:99], v[68:69], v[88:89] op_sel:[0,1,0]
	v_pk_fma_f32 v[90:91], v[98:99], v[70:71], v[90:91] op_sel_hi:[1,0,1]
	v_pk_fma_f32 v[92:93], v[98:99], v[70:71], v[92:93] op_sel:[0,1,0]
	v_pk_fma_f32 v[94:95], v[98:99], v[72:73], v[94:95] op_sel_hi:[1,0,1]
	v_pk_fma_f32 v[96:97], v[98:99], v[72:73], v[96:97] op_sel:[0,1,0]
	v_pk_fma_f32 v[82:83], v[108:109], v[58:59], v[82:83] op_sel_hi:[1,0,1]
	v_pk_fma_f32 v[84:85], v[108:109], v[58:59], v[84:85] op_sel:[0,1,0]
	v_pk_fma_f32 v[86:87], v[108:109], v[60:61], v[86:87] op_sel_hi:[1,0,1]
	v_pk_fma_f32 v[88:89], v[108:109], v[60:61], v[88:89] op_sel:[0,1,0]
	v_pk_fma_f32 v[90:91], v[108:109], v[62:63], v[90:91] op_sel_hi:[1,0,1]
	v_pk_fma_f32 v[92:93], v[108:109], v[62:63], v[92:93] op_sel:[0,1,0]
	v_pk_fma_f32 v[94:95], v[108:109], v[64:65], v[94:95] op_sel_hi:[1,0,1]
	v_pk_fma_f32 v[96:97], v[108:109], v[64:65], v[96:97] op_sel:[0,1,0]
	v_pk_mul_f32 v[108:109], v[82:83], v[0:1] op_sel_hi:[1,0]
	v_pk_mul_f32 v[110:111], v[82:83], v[74:75] op_sel_hi:[1,0]
	v_pk_fma_f32 v[108:109], v[84:85], v[0:1], v[108:109] op_sel:[0,1,0]
	v_pk_fma_f32 v[110:111], v[84:85], v[74:75], v[110:111] op_sel:[0,1,0]
	v_pk_fma_f32 v[108:109], v[86:87], v[2:3], v[108:109] op_sel_hi:[1,0,1]
	v_pk_fma_f32 v[110:111], v[86:87], v[76:77], v[110:111] op_sel_hi:[1,0,1]
	v_pk_fma_f32 v[108:109], v[88:89], v[2:3], v[108:109] op_sel:[0,1,0]
	v_pk_fma_f32 v[110:111], v[88:89], v[76:77], v[110:111] op_sel:[0,1,0]
	v_pk_fma_f32 v[108:109], v[90:91], v[4:5], v[108:109] op_sel_hi:[1,0,1]
	v_pk_fma_f32 v[110:111], v[90:91], v[78:79], v[110:111] op_sel_hi:[1,0,1]
	v_pk_fma_f32 v[108:109], v[92:93], v[4:5], v[108:109] op_sel:[0,1,0]
	v_pk_fma_f32 v[110:111], v[92:93], v[78:79], v[110:111] op_sel:[0,1,0]
	v_pk_fma_f32 v[108:109], v[94:95], v[6:7], v[108:109] op_sel_hi:[1,0,1]
	v_pk_fma_f32 v[110:111], v[94:95], v[80:81], v[110:111] op_sel_hi:[1,0,1]
	v_pk_fma_f32 v[108:109], v[96:97], v[6:7], v[108:109] op_sel:[0,1,0]
	v_pk_fma_f32 v[110:111], v[96:97], v[80:81], v[110:111] op_sel:[0,1,0]
	ds_read_b128 v[42:45], v107 offset:13824
	ds_read_b128 v[46:49], v107 offset:13840
	ds_read_b128 v[50:53], v107 offset:14080
	ds_read_b128 v[54:57], v107 offset:14096
	ds_read_b128 v[66:69], v107 offset:14592
	ds_read_b128 v[70:73], v107 offset:14608
	ds_read_b64 v[98:99], v106 offset:15104
	ds_read_b128 v[58:61], v107 offset:14336
	ds_read_b128 v[62:65], v107 offset:14352
	ds_read_b128 v[74:77], v107 offset:14848
	ds_read_b128 v[78:81], v107 offset:14864
	v_add_f32_dpp v108, v108, v108 quad_perm:[1,0,3,2] row_mask:0xf bank_mask:0xf bound_ctrl:1
	v_add_f32_dpp v109, v109, v109 quad_perm:[1,0,3,2] row_mask:0xf bank_mask:0xf bound_ctrl:1
	v_add_f32_dpp v110, v110, v110 quad_perm:[1,0,3,2] row_mask:0xf bank_mask:0xf bound_ctrl:1
	v_add_f32_dpp v111, v111, v111 quad_perm:[1,0,3,2] row_mask:0xf bank_mask:0xf bound_ctrl:1
	v_add_f32_dpp v108, v108, v108 quad_perm:[2,3,0,1] row_mask:0xf bank_mask:0xf bound_ctrl:1
	v_add_f32_dpp v109, v109, v109 quad_perm:[2,3,0,1] row_mask:0xf bank_mask:0xf bound_ctrl:1
	v_add_f32_dpp v110, v110, v110 quad_perm:[2,3,0,1] row_mask:0xf bank_mask:0xf bound_ctrl:1
	v_add_f32_dpp v111, v111, v111 quad_perm:[2,3,0,1] row_mask:0xf bank_mask:0xf bound_ctrl:1
	v_add_f32_dpp v108, v108, v108 row_half_mirror row_mask:0xf bank_mask:0xf bound_ctrl:1
	v_add_f32_dpp v109, v109, v109 row_half_mirror row_mask:0xf bank_mask:0xf bound_ctrl:1
	v_add_f32_dpp v110, v110, v110 row_half_mirror row_mask:0xf bank_mask:0xf bound_ctrl:1
	v_add_f32_dpp v111, v111, v111 row_half_mirror row_mask:0xf bank_mask:0xf bound_ctrl:1
	ds_write_b64 v105, v[110:111] offset:1792
	s_add_i32 s7, s7, -8
	v_add_u32_e32 v107, 0x3000, v107
	v_add_u32_e32 v106, 0x3000, v106
	v_add_u32_e32 v105, 0x800, v105
	s_cmp_eq_u32 s7, 0
	s_cbranch_scc0 .Lscnp_loop
	s_branch .LBB0_411

; #define LAS __attribute__((address_space(3)))
; template <int CTRL> __device__ __forceinline__ float dpp_f(float v) { return __builtin_bit_cast(float, __builtin_amdgcn_update_dpp(0, __builtin_bit_cast(int, v), CTRL, 0xF, 0xF, true)); }
; template <int R>
; __device__ __forceinline__ void scan_item(const Args& a, int layer, int q, int rowhalf, LAS unsigned char* lds, int tid, int lane, int wave) {
;     ...
;             for (int s = 0; s < SC_CH; ++s) {
;                 const LAS f32x4* on = op + (s + 1) * 96;
;                 const f32x4 na0 = on[2 * ci], na1 = on[2 * ci + 1], nw0 = on[16 + 2 * ci], nw1 = on[17 + 2 * ci], nb0 = on[32 + 2 * ci], nb1 = on[33 + 2 * ci];
;                 const f32x4 nk0 = on[48 + 2 * ci], nk1 = on[49 + 2 * ci], nr0 = on[64 + 2 * ci], nr1 = on[65 + 2 * ci]; const vecR nv4 = *(const LAS vecR*)((const LAS float*)on + 320 + vrow);
;                 const f32x2 av[4] = {{a0.x, a0.y}, {a0.z, a0.w}, {a1.x, a1.y}, {a1.z, a1.w}}, wv[4] = {{w0.x, w0.y}, {w0.z, w0.w}, {w1.x, w1.y}, {w1.z, w1.w}};
;                 const f32x2 bv[4] = {{b0.x, b0.y}, {b0.z, b0.w}, {b1.x, b1.y}, {b1.z, b1.w}}, kv[4] = {{k0.x, k0.y}, {k0.z, k0.w}, {k1.x, k1.y}, {k1.z, k1.w}};
;                 const f32x2 rv[4] = {{r0.x, r0.y}, {r0.z, r0.w}, {r1.x, r1.y}, {r1.z, r1.w}};
;                 float sa[RL];
; #pragma unroll
;                 for (int i = 0; i < RL; ++i) { f32x2 p = S[i][0] * av[0]; p = S[i][1] * av[1] + p; p = S[i][2] * av[2] + p; p = S[i][3] * av[3] + p;
;                     float t = p.x + p.y; t += dpp_f<0xB1>(t); t += dpp_f<0x4E>(t); t += dpp_f<0x141>(t); sa[i] = t; }
;                 vecR y;
; #pragma unroll
;                 for (int i = 0; i < RL; ++i) { const f32x2 sa2 = {sa[i], sa[i]}, v2 = {v4[i], v4[i]};
; #pragma unroll
;                     for (int c2 = 0; c2 < 4; ++c2) S[i][c2] = S[i][c2] * wv[c2] + sa2 * bv[c2] + v2 * kv[c2];
;                     f32x2 p = S[i][0] * rv[0]; p = S[i][1] * rv[1] + p; p = S[i][2] * rv[2] + p; p = S[i][3] * rv[3] + p;
;                     float t = p.x + p.y; t += dpp_f<0xB1>(t); t += dpp_f<0x4E>(t); t += dpp_f<0x141>(t); y[i] = t; }
;                 if (ci == 0) *(LAS vecR*)(yb + s * (32 * RL) + yrow) = y;
;                 a0 = na0; a1 = na1; w0 = nw0; w1 = nw1; b0 = nb0; b1 = nb1; k0 = nk0; k1 = nk1; r0 = nr0; r1 = nr1; v4 = nv4;
;             }
.Lscnh_loop:
	s_waitcnt lgkmcnt(9)
	v_pk_mul_f32 v[80:81], v[80:81], v[8:9]
	v_pk_mul_f32 v[82:83], v[82:83], v[10:11]
	v_pk_mul_f32 v[84:85], v[84:85], v[12:13]
	v_pk_mul_f32 v[86:87], v[86:87], v[14:15]
	v_pk_fma_f32 v[80:81], v[88:89], v[24:25], v[80:81] op_sel_hi:[0,1,1]
	v_pk_fma_f32 v[82:83], v[88:89], v[26:27], v[82:83] op_sel_hi:[0,1,1]
	v_pk_fma_f32 v[84:85], v[88:89], v[28:29], v[84:85] op_sel_hi:[0,1,1]
	v_pk_fma_f32 v[86:87], v[88:89], v[30:31], v[86:87] op_sel_hi:[0,1,1]
	v_pk_fma_f32 v[80:81], v[98:99], v[16:17], v[80:81] op_sel_hi:[0,1,1]
	v_pk_fma_f32 v[82:83], v[98:99], v[18:19], v[82:83] op_sel_hi:[0,1,1]
	v_pk_fma_f32 v[84:85], v[98:99], v[20:21], v[84:85] op_sel_hi:[0,1,1]
	v_pk_fma_f32 v[86:87], v[98:99], v[22:23], v[86:87] op_sel_hi:[0,1,1]
	v_pk_mul_f32 v[98:99], v[80:81], v[40:41]
	v_pk_mul_f32 v[100:101], v[80:81], v[32:33]
	v_pk_fma_f32 v[98:99], v[82:83], v[42:43], v[98:99]
	v_pk_fma_f32 v[100:101], v[82:83], v[34:35], v[100:101]
	v_pk_fma_f32 v[98:99], v[84:85], v[44:45], v[98:99]
	v_pk_fma_f32 v[100:101], v[84:85], v[36:37], v[100:101]
	v_pk_fma_f32 v[98:99], v[86:87], v[46:47], v[98:99]
	v_pk_fma_f32 v[100:101], v[86:87], v[38:39], v[100:101]
	v_add_f32_e32 v98, v98, v99
	v_add_f32_e32 v100, v100, v101
	ds_read_b128 v[0:3], v97 offset:3072
	ds_read_b128 v[4:7], v97 offset:3088
	v_add_f32_dpp v98, v98, v98 quad_perm:[1,0,3,2] row_mask:0xf bank_mask:0xf bound_ctrl:1
	v_add_f32_dpp v100, v100, v100 quad_perm:[1,0,3,2] row_mask:0xf bank_mask:0xf bound_ctrl:1
	ds_read_b128 v[8:11], v97 offset:3328
	ds_read_b128 v[12:15], v97 offset:3344
	v_add_f32_dpp v98, v98, v98 quad_perm:[2,3,0,1] row_mask:0xf bank_mask:0xf bound_ctrl:1
	v_add_f32_dpp v100, v100, v100 quad_perm:[2,3,0,1] row_mask:0xf bank_mask:0xf bound_ctrl:1
	ds_read_b128 v[24:27], v97 offset:3840
	ds_read_b128 v[28:31], v97 offset:3856
	v_add_f32_dpp v98, v98, v98 row_half_mirror row_mask:0xf bank_mask:0xf bound_ctrl:1
	v_add_f32_dpp v100, v100, v100 row_half_mirror row_mask:0xf bank_mask:0xf bound_ctrl:1
	ds_read_b32 v88, v102 offset:4352
	ds_read_b128 v[16:19], v97 offset:3584
	ds_read_b128 v[20:23], v97 offset:3600
	ds_read_b128 v[32:35], v97 offset:4096
	ds_read_b128 v[36:39], v97 offset:4112
	ds_write_b32 v89, v100 offset:0
	s_waitcnt lgkmcnt(9)
	v_pk_mul_f32 v[80:81], v[80:81], v[48:49]
	v_pk_mul_f32 v[82:83], v[82:83], v[50:51]
	v_pk_mul_f32 v[84:85], v[84:85], v[52:53]
	v_pk_mul_f32 v[86:87], v[86:87], v[54:55]
	v_pk_fma_f32 v[80:81], v[90:91], v[64:65], v[80:81] op_sel_hi:[0,1,1]
	v_pk_fma_f32 v[82:83], v[90:91], v[66:67], v[82:83] op_sel_hi:[0,1,1]
	v_pk_fma_f32 v[84:85], v[90:91], v[68:69], v[84:85] op_sel_hi:[0,1,1]
	v_pk_fma_f32 v[86:87], v[90:91], v[70:71], v[86:87] op_sel_hi:[0,1,1]
	v_pk_fma_f32 v[80:81], v[98:99], v[56:57], v[80:81] op_sel_hi:[0,1,1]
	v_pk_fma_f32 v[82:83], v[98:99], v[58:59], v[82:83] op_sel_hi:[0,1,1]
	v_pk_fma_f32 v[84:85], v[98:99], v[60:61], v[84:85] op_sel_hi:[0,1,1]
	v_pk_fma_f32 v[86:87], v[98:99], v[62:63], v[86:87] op_sel_hi:[0,1,1]
	v_pk_mul_f32 v[98:99], v[80:81], v[0:1]
	v_pk_mul_f32 v[100:101], v[80:81], v[72:73]
	v_pk_fma_f32 v[98:99], v[82:83], v[2:3], v[98:99]
	v_pk_fma_f32 v[100:101], v[82:83], v[74:75], v[100:101]
	v_pk_fma_f32 v[98:99], v[84:85], v[4:5], v[98:99]
	v_pk_fma_f32 v[100:101], v[84:85], v[76:77], v[100:101]
	v_pk_fma_f32 v[98:99], v[86:87], v[6:7], v[98:99]
	v_pk_fma_f32 v[100:101], v[86:87], v[78:79], v[100:101]
	v_add_f32_e32 v98, v98, v99
	v_add_f32_e32 v100, v100, v101
	ds_read_b128 v[40:43], v97 offset:4608
	ds_read_b128 v[44:47], v97 offset:4624
	v_add_f32_dpp v98, v98, v98 quad_perm:[1,0,3,2] row_mask:0xf bank_mask:0xf bound_ctrl:1
	v_add_f32_dpp v100, v100, v100 quad_perm:[1,0,3,2] row_mask:0xf bank_mask:0xf bound_ctrl:1
	ds_read_b128 v[48:51], v97 offset:4864
	ds_read_b128 v[52:55], v97 offset:4880
	v_add_f32_dpp v98, v98, v98 quad_perm:[2,3,0,1] row_mask:0xf bank_mask:0xf bound_ctrl:1
	v_add_f32_dpp v100, v100, v100 quad_perm:[2,3,0,1] row_mask:0xf bank_mask:0xf bound_ctrl:1
	ds_read_b128 v[64:67], v97 offset:5376
	ds_read_b128 v[68:71], v97 offset:5392
	v_add_f32_dpp v98, v98, v98 row_half_mirror row_mask:0xf bank_mask:0xf bound_ctrl:1
	v_add_f32_dpp v100, v100, v100 row_half_mirror row_mask:0xf bank_mask:0xf bound_ctrl:1
	ds_read_b32 v90, v102 offset:5888
	ds_read_b128 v[56:59], v97 offset:5120
	ds_read_b128 v[60:63], v97 offset:5136
	ds_read_b128 v[72:75], v97 offset:5632
	ds_read_b128 v[76:79], v97 offset:5648
	ds_write_b32 v89, v100 offset:128
	s_waitcnt lgkmcnt(9)
	v_pk_mul_f32 v[80:81], v[80:81], v[8:9]
	v_pk_mul_f32 v[82:83], v[82:83], v[10:11]
	v_pk_mul_f32 v[84:85], v[84:85], v[12:13]
	v_pk_mul_f32 v[86:87], v[86:87], v[14:15]
	v_pk_fma_f32 v[80:81], v[88:89], v[24:25], v[80:81] op_sel_hi:[0,1,1]
	v_pk_fma_f32 v[82:83], v[88:89], v[26:27], v[82:83] op_sel_hi:[0,1,1]
	v_pk_fma_f32 v[84:85], v[88:89], v[28:29], v[84:85] op_sel_hi:[0,1,1]
	v_pk_fma_f32 v[86:87], v[88:89], v[30:31], v[86:87] op_sel_hi:[0,1,1]
	v_pk_fma_f32 v[80:81], v[98:99], v[16:17], v[80:81] op_sel_hi:[0,1,1]
	v_pk_fma_f32 v[82:83], v[98:99], v[18:19], v[82:83] op_sel_hi:[0,1,1]
	v_pk_fma_f32 v[84:85], v[98:99], v[20:21], v[84:85] op_sel_hi:[0,1,1]
	v_pk_fma_f32 v[86:87], v[98:99], v[22:23], v[86:87] op_sel_hi:[0,1,1]
	v_pk_mul_f32 v[98:99], v[80:81], v[40:41]
	v_pk_mul_f32 v[100:101], v[80:81], v[32:33]
	v_pk_fma_f32 v[98:99], v[82:83], v[42:43], v[98:99]
	v_pk_fma_f32 v[100:101], v[82:83], v[34:35], v[100:101]
	v_pk_fma_f32 v[98:99], v[84:85], v[44:45], v[98:99]
	v_pk_fma_f32 v[100:101], v[84:85], v[36:37], v[100:101]
	v_pk_fma_f32 v[98:99], v[86:87], v[46:47], v[98:99]
	v_pk_fma_f32 v[100:101], v[86:87], v[38:39], v[100:101]
	v_add_f32_e32 v98, v98, v99
	v_add_f32_e32 v100, v100, v101
	ds_read_b128 v[0:3], v97 offset:6144
	ds_read_b128 v[4:7], v97 offset:6160
	v_add_f32_dpp v98, v98, v98 quad_perm:[1,0,3,2] row_mask:0xf bank_mask:0xf bound_ctrl:1
	v_add_f32_dpp v100, v100, v100 quad_perm:[1,0,3,2] row_mask:0xf bank_mask:0xf bound_ctrl:1
	ds_read_b128 v[8:11], v97 offset:6400
	ds_read_b128 v[12:15], v97 offset:6416
	v_add_f32_dpp v98, v98, v98 quad_perm:[2,3,0,1] row_mask:0xf bank_mask:0xf bound_ctrl:1
	v_add_f32_dpp v100, v100, v100 quad_perm:[2,3,0,1] row_mask:0xf bank_mask:0xf bound_ctrl:1
	ds_read_b128 v[24:27], v97 offset:6912
	ds_read_b128 v[28:31], v97 offset:6928
	v_add_f32_dpp v98, v98, v98 row_half_mirror row_mask:0xf bank_mask:0xf bound_ctrl:1
	v_add_f32_dpp v100, v100, v100 row_half_mirror row_mask:0xf bank_mask:0xf bound_ctrl:1
	ds_read_b32 v88, v102 offset:7424
	ds_read_b128 v[16:19], v97 offset:6656
	ds_read_b128 v[20:23], v97 offset:6672
	ds_read_b128 v[32:35], v97 offset:7168
	ds_read_b128 v[36:39], v97 offset:7184
	ds_write_b32 v89, v100 offset:256
	s_waitcnt lgkmcnt(9)
; #define LAS __attribute__((address_space(3)))
; template <int CTRL> __device__ __forceinline__ float dpp_f(float v) { return __builtin_bit_cast(float, __builtin_amdgcn_update_dpp(0, __builtin_bit_cast(int, v), CTRL, 0xF, 0xF, true)); }
; template <int R>
; __device__ __forceinline__ void scan_item(const Args& a, int layer, int q, int rowhalf, LAS unsigned char* lds, int tid, int lane, int wave) {
;     ...
;             for (int s = 0; s < SC_CH; ++s) {
;                 const LAS f32x4* on = op + (s + 1) * 96;
;                 const f32x4 na0 = on[2 * ci], na1 = on[2 * ci + 1], nw0 = on[16 + 2 * ci], nw1 = on[17 + 2 * ci], nb0 = on[32 + 2 * ci], nb1 = on[33 + 2 * ci];
;                 const f32x4 nk0 = on[48 + 2 * ci], nk1 = on[49 + 2 * ci], nr0 = on[64 + 2 * ci], nr1 = on[65 + 2 * ci]; const vecR nv4 = *(const LAS vecR*)((const LAS float*)on + 320 + vrow);
;                 const f32x2 av[4] = {{a0.x, a0.y}, {a0.z, a0.w}, {a1.x, a1.y}, {a1.z, a1.w}}, wv[4] = {{w0.x, w0.y}, {w0.z, w0.w}, {w1.x, w1.y}, {w1.z, w1.w}};
;                 const f32x2 bv[4] = {{b0.x, b0.y}, {b0.z, b0.w}, {b1.x, b1.y}, {b1.z, b1.w}}, kv[4] = {{k0.x, k0.y}, {k0.z, k0.w}, {k1.x, k1.y}, {k1.z, k1.w}};
;                 const f32x2 rv[4] = {{r0.x, r0.y}, {r0.z, r0.w}, {r1.x, r1.y}, {r1.z, r1.w}};
;                 float sa[RL];
; #pragma unroll
;                 for (int i = 0; i < RL; ++i) { f32x2 p = S[i][0] * av[0]; p = S[i][1] * av[1] + p; p = S[i][2] * av[2] + p; p = S[i][3] * av[3] + p;
;                     float t = p.x + p.y; t += dpp_f<0xB1>(t); t += dpp_f<0x4E>(t); t += dpp_f<0x141>(t); sa[i] = t; }
;                 vecR y;
; #pragma unroll
;                 for (int i = 0; i < RL; ++i) { const f32x2 sa2 = {sa[i], sa[i]}, v2 = {v4[i], v4[i]};
; #pragma unroll
;                     for (int c2 = 0; c2 < 4; ++c2) S[i][c2] = S[i][c2] * wv[c2] + sa2 * bv[c2] + v2 * kv[c2];
;                     f32x2 p = S[i][0] * rv[0]; p = S[i][1] * rv[1] + p; p = S[i][2] * rv[2] + p; p = S[i][3] * rv[3] + p;
;                     float t = p.x + p.y; t += dpp_f<0xB1>(t); t += dpp_f<0x4E>(t); t += dpp_f<0x141>(t); y[i] = t; }
;                 if (ci == 0) *(LAS vecR*)(yb + s * (32 * RL) + yrow) = y;
;                 a0 = na0; a1 = na1; w0 = nw0; w1 = nw1; b0 = nb0; b1 = nb1; k0 = nk0; k1 = nk1; r0 = nr0; r1 = nr1; v4 = nv4;
;             }
	v_pk_mul_f32 v[80:81], v[80:81], v[48:49]
	v_pk_mul_f32 v[82:83], v[82:83], v[50:51]
	v_pk_mul_f32 v[84:85], v[84:85], v[52:53]
	v_pk_mul_f32 v[86:87], v[86:87], v[54:55]
	v_pk_fma_f32 v[80:81], v[90:91], v[64:65], v[80:81] op_sel_hi:[0,1,1]
	v_pk_fma_f32 v[82:83], v[90:91], v[66:67], v[82:83] op_sel_hi:[0,1,1]
	v_pk_fma_f32 v[84:85], v[90:91], v[68:69], v[84:85] op_sel_hi:[0,1,1]
	v_pk_fma_f32 v[86:87], v[90:91], v[70:71], v[86:87] op_sel_hi:[0,1,1]
	v_pk_fma_f32 v[80:81], v[98:99], v[56:57], v[80:81] op_sel_hi:[0,1,1]
	v_pk_fma_f32 v[82:83], v[98:99], v[58:59], v[82:83] op_sel_hi:[0,1,1]
	v_pk_fma_f32 v[84:85], v[98:99], v[60:61], v[84:85] op_sel_hi:[0,1,1]
	v_pk_fma_f32 v[86:87], v[98:99], v[62:63], v[86:87] op_sel_hi:[0,1,1]
	v_pk_mul_f32 v[98:99], v[80:81], v[0:1]
	v_pk_mul_f32 v[100:101], v[80:81], v[72:73]
	v_pk_fma_f32 v[98:99], v[82:83], v[2:3], v[98:99]
	v_pk_fma_f32 v[100:101], v[82:83], v[74:75], v[100:101]
	v_pk_fma_f32 v[98:99], v[84:85], v[4:5], v[98:99]
	v_pk_fma_f32 v[100:101], v[84:85], v[76:77], v[100:101]
	v_pk_fma_f32 v[98:99], v[86:87], v[6:7], v[98:99]
	v_pk_fma_f32 v[100:101], v[86:87], v[78:79], v[100:101]
	v_add_f32_e32 v98, v98, v99
	v_add_f32_e32 v100, v100, v101
	ds_read_b128 v[40:43], v97 offset:7680
	ds_read_b128 v[44:47], v97 offset:7696
	v_add_f32_dpp v98, v98, v98 quad_perm:[1,0,3,2] row_mask:0xf bank_mask:0xf bound_ctrl:1
	v_add_f32_dpp v100, v100, v100 quad_perm:[1,0,3,2] row_mask:0xf bank_mask:0xf bound_ctrl:1
	ds_read_b128 v[48:51], v97 offset:7936
	ds_read_b128 v[52:55], v97 offset:7952
	v_add_f32_dpp v98, v98, v98 quad_perm:[2,3,0,1] row_mask:0xf bank_mask:0xf bound_ctrl:1
	v_add_f32_dpp v100, v100, v100 quad_perm:[2,3,0,1] row_mask:0xf bank_mask:0xf bound_ctrl:1
	ds_read_b128 v[64:67], v97 offset:8448
	ds_read_b128 v[68:71], v97 offset:8464
	v_add_f32_dpp v98, v98, v98 row_half_mirror row_mask:0xf bank_mask:0xf bound_ctrl:1
	v_add_f32_dpp v100, v100, v100 row_half_mirror row_mask:0xf bank_mask:0xf bound_ctrl:1
	ds_read_b32 v90, v102 offset:8960
	ds_read_b128 v[56:59], v97 offset:8192
	ds_read_b128 v[60:63], v97 offset:8208
	ds_read_b128 v[72:75], v97 offset:8704
	ds_read_b128 v[76:79], v97 offset:8720
	ds_write_b32 v89, v100 offset:384
	s_waitcnt lgkmcnt(9)
	v_pk_mul_f32 v[80:81], v[80:81], v[8:9]
	v_pk_mul_f32 v[82:83], v[82:83], v[10:11]
	v_pk_mul_f32 v[84:85], v[84:85], v[12:13]
	v_pk_mul_f32 v[86:87], v[86:87], v[14:15]
	v_pk_fma_f32 v[80:81], v[88:89], v[24:25], v[80:81] op_sel_hi:[0,1,1]
	v_pk_fma_f32 v[82:83], v[88:89], v[26:27], v[82:83] op_sel_hi:[0,1,1]
	v_pk_fma_f32 v[84:85], v[88:89], v[28:29], v[84:85] op_sel_hi:[0,1,1]
	v_pk_fma_f32 v[86:87], v[88:89], v[30:31], v[86:87] op_sel_hi:[0,1,1]
	v_pk_fma_f32 v[80:81], v[98:99], v[16:17], v[80:81] op_sel_hi:[0,1,1]
	v_pk_fma_f32 v[82:83], v[98:99], v[18:19], v[82:83] op_sel_hi:[0,1,1]
	v_pk_fma_f32 v[84:85], v[98:99], v[20:21], v[84:85] op_sel_hi:[0,1,1]
	v_pk_fma_f32 v[86:87], v[98:99], v[22:23], v[86:87] op_sel_hi:[0,1,1]
	v_pk_mul_f32 v[98:99], v[80:81], v[40:41]
	v_pk_mul_f32 v[100:101], v[80:81], v[32:33]
	v_pk_fma_f32 v[98:99], v[82:83], v[42:43], v[98:99]
	v_pk_fma_f32 v[100:101], v[82:83], v[34:35], v[100:101]
	v_pk_fma_f32 v[98:99], v[84:85], v[44:45], v[98:99]
	v_pk_fma_f32 v[100:101], v[84:85], v[36:37], v[100:101]
	v_pk_fma_f32 v[98:99], v[86:87], v[46:47], v[98:99]
	v_pk_fma_f32 v[100:101], v[86:87], v[38:39], v[100:101]
	v_add_f32_e32 v98, v98, v99
	v_add_f32_e32 v100, v100, v101
	ds_read_b128 v[0:3], v97 offset:9216
	ds_read_b128 v[4:7], v97 offset:9232
	v_add_f32_dpp v98, v98, v98 quad_perm:[1,0,3,2] row_mask:0xf bank_mask:0xf bound_ctrl:1
	v_add_f32_dpp v100, v100, v100 quad_perm:[1,0,3,2] row_mask:0xf bank_mask:0xf bound_ctrl:1
	ds_read_b128 v[8:11], v97 offset:9472
	ds_read_b128 v[12:15], v97 offset:9488
	v_add_f32_dpp v98, v98, v98 quad_perm:[2,3,0,1] row_mask:0xf bank_mask:0xf bound_ctrl:1
	v_add_f32_dpp v100, v100, v100 quad_perm:[2,3,0,1] row_mask:0xf bank_mask:0xf bound_ctrl:1
	ds_read_b128 v[24:27], v97 offset:9984
	ds_read_b128 v[28:31], v97 offset:10000
	v_add_f32_dpp v98, v98, v98 row_half_mirror row_mask:0xf bank_mask:0xf bound_ctrl:1
	v_add_f32_dpp v100, v100, v100 row_half_mirror row_mask:0xf bank_mask:0xf bound_ctrl:1
	ds_read_b32 v88, v102 offset:10496
	ds_read_b128 v[16:19], v97 offset:9728
	ds_read_b128 v[20:23], v97 offset:9744
	ds_read_b128 v[32:35], v97 offset:10240
	ds_read_b128 v[36:39], v97 offset:10256
	ds_write_b32 v89, v100 offset:512
	s_waitcnt lgkmcnt(9)
	v_pk_mul_f32 v[80:81], v[80:81], v[48:49]
	v_pk_mul_f32 v[82:83], v[82:83], v[50:51]
	v_pk_mul_f32 v[84:85], v[84:85], v[52:53]
	v_pk_mul_f32 v[86:87], v[86:87], v[54:55]
	v_pk_fma_f32 v[80:81], v[90:91], v[64:65], v[80:81] op_sel_hi:[0,1,1]
	v_pk_fma_f32 v[82:83], v[90:91], v[66:67], v[82:83] op_sel_hi:[0,1,1]
	v_pk_fma_f32 v[84:85], v[90:91], v[68:69], v[84:85] op_sel_hi:[0,1,1]
	v_pk_fma_f32 v[86:87], v[90:91], v[70:71], v[86:87] op_sel_hi:[0,1,1]
	v_pk_fma_f32 v[80:81], v[98:99], v[56:57], v[80:81] op_sel_hi:[0,1,1]
	v_pk_fma_f32 v[82:83], v[98:99], v[58:59], v[82:83] op_sel_hi:[0,1,1]
	v_pk_fma_f32 v[84:85], v[98:99], v[60:61], v[84:85] op_sel_hi:[0,1,1]
	v_pk_fma_f32 v[86:87], v[98:99], v[62:63], v[86:87] op_sel_hi:[0,1,1]
	v_pk_mul_f32 v[98:99], v[80:81], v[0:1]
	v_pk_mul_f32 v[100:101], v[80:81], v[72:73]
	v_pk_fma_f32 v[98:99], v[82:83], v[2:3], v[98:99]
	v_pk_fma_f32 v[100:101], v[82:83], v[74:75], v[100:101]
	v_pk_fma_f32 v[98:99], v[84:85], v[4:5], v[98:99]
	v_pk_fma_f32 v[100:101], v[84:85], v[76:77], v[100:101]
	v_pk_fma_f32 v[98:99], v[86:87], v[6:7], v[98:99]
	v_pk_fma_f32 v[100:101], v[86:87], v[78:79], v[100:101]
	v_add_f32_e32 v98, v98, v99
	v_add_f32_e32 v100, v100, v101
	ds_read_b128 v[40:43], v97 offset:10752
	ds_read_b128 v[44:47], v97 offset:10768
	v_add_f32_dpp v98, v98, v98 quad_perm:[1,0,3,2] row_mask:0xf bank_mask:0xf bound_ctrl:1
	v_add_f32_dpp v100, v100, v100 quad_perm:[1,0,3,2] row_mask:0xf bank_mask:0xf bound_ctrl:1
	ds_read_b128 v[48:51], v97 offset:11008
	ds_read_b128 v[52:55], v97 offset:11024
	v_add_f32_dpp v98, v98, v98 quad_perm:[2,3,0,1] row_mask:0xf bank_mask:0xf bound_ctrl:1
	v_add_f32_dpp v100, v100, v100 quad_perm:[2,3,0,1] row_mask:0xf bank_mask:0xf bound_ctrl:1
	ds_read_b128 v[64:67], v97 offset:11520
	ds_read_b128 v[68:71], v97 offset:11536
	v_add_f32_dpp v98, v98, v98 row_half_mirror row_mask:0xf bank_mask:0xf bound_ctrl:1
	v_add_f32_dpp v100, v100, v100 row_half_mirror row_mask:0xf bank_mask:0xf bound_ctrl:1
	ds_read_b32 v90, v102 offset:12032
	ds_read_b128 v[56:59], v97 offset:11264
	ds_read_b128 v[60:63], v97 offset:11280
	ds_read_b128 v[72:75], v97 offset:11776
	ds_read_b128 v[76:79], v97 offset:11792
	ds_write_b32 v89, v100 offset:640
	s_waitcnt lgkmcnt(9)
; #define LAS __attribute__((address_space(3)))
; template <int CTRL> __device__ __forceinline__ float dpp_f(float v) { return __builtin_bit_cast(float, __builtin_amdgcn_update_dpp(0, __builtin_bit_cast(int, v), CTRL, 0xF, 0xF, true)); }
; template <int R>
; __device__ __forceinline__ void scan_item(const Args& a, int layer, int q, int rowhalf, LAS unsigned char* lds, int tid, int lane, int wave) {
;     ...
;             for (int s = 0; s < SC_CH; ++s) {
;                 const LAS f32x4* on = op + (s + 1) * 96;
;                 const f32x4 na0 = on[2 * ci], na1 = on[2 * ci + 1], nw0 = on[16 + 2 * ci], nw1 = on[17 + 2 * ci], nb0 = on[32 + 2 * ci], nb1 = on[33 + 2 * ci];
;                 const f32x4 nk0 = on[48 + 2 * ci], nk1 = on[49 + 2 * ci], nr0 = on[64 + 2 * ci], nr1 = on[65 + 2 * ci]; const vecR nv4 = *(const LAS vecR*)((const LAS float*)on + 320 + vrow);
;                 const f32x2 av[4] = {{a0.x, a0.y}, {a0.z, a0.w}, {a1.x, a1.y}, {a1.z, a1.w}}, wv[4] = {{w0.x, w0.y}, {w0.z, w0.w}, {w1.x, w1.y}, {w1.z, w1.w}};
;                 const f32x2 bv[4] = {{b0.x, b0.y}, {b0.z, b0.w}, {b1.x, b1.y}, {b1.z, b1.w}}, kv[4] = {{k0.x, k0.y}, {k0.z, k0.w}, {k1.x, k1.y}, {k1.z, k1.w}};
;                 const f32x2 rv[4] = {{r0.x, r0.y}, {r0.z, r0.w}, {r1.x, r1.y}, {r1.z, r1.w}};
;                 float sa[RL];
; #pragma unroll
;                 for (int i = 0; i < RL; ++i) { f32x2 p = S[i][0] * av[0]; p = S[i][1] * av[1] + p; p = S[i][2] * av[2] + p; p = S[i][3] * av[3] + p;
;                     float t = p.x + p.y; t += dpp_f<0xB1>(t); t += dpp_f<0x4E>(t); t += dpp_f<0x141>(t); sa[i] = t; }
;                 vecR y;
; #pragma unroll
;                 for (int i = 0; i < RL; ++i) { const f32x2 sa2 = {sa[i], sa[i]}, v2 = {v4[i], v4[i]};
; #pragma unroll
;                     for (int c2 = 0; c2 < 4; ++c2) S[i][c2] = S[i][c2] * wv[c2] + sa2 * bv[c2] + v2 * kv[c2];
;                     f32x2 p = S[i][0] * rv[0]; p = S[i][1] * rv[1] + p; p = S[i][2] * rv[2] + p; p = S[i][3] * rv[3] + p;
;                     float t = p.x + p.y; t += dpp_f<0xB1>(t); t += dpp_f<0x4E>(t); t += dpp_f<0x141>(t); y[i] = t; }
;                 if (ci == 0) *(LAS vecR*)(yb + s * (32 * RL) + yrow) = y;
;                 a0 = na0; a1 = na1; w0 = nw0; w1 = nw1; b0 = nb0; b1 = nb1; k0 = nk0; k1 = nk1; r0 = nr0; r1 = nr1; v4 = nv4;
;             }
	v_pk_mul_f32 v[80:81], v[80:81], v[8:9]
	v_pk_mul_f32 v[82:83], v[82:83], v[10:11]
	v_pk_mul_f32 v[84:85], v[84:85], v[12:13]
	v_pk_mul_f32 v[86:87], v[86:87], v[14:15]
	v_pk_fma_f32 v[80:81], v[88:89], v[24:25], v[80:81] op_sel_hi:[0,1,1]
	v_pk_fma_f32 v[82:83], v[88:89], v[26:27], v[82:83] op_sel_hi:[0,1,1]
	v_pk_fma_f32 v[84:85], v[88:89], v[28:29], v[84:85] op_sel_hi:[0,1,1]
	v_pk_fma_f32 v[86:87], v[88:89], v[30:31], v[86:87] op_sel_hi:[0,1,1]
	v_pk_fma_f32 v[80:81], v[98:99], v[16:17], v[80:81] op_sel_hi:[0,1,1]
	v_pk_fma_f32 v[82:83], v[98:99], v[18:19], v[82:83] op_sel_hi:[0,1,1]
	v_pk_fma_f32 v[84:85], v[98:99], v[20:21], v[84:85] op_sel_hi:[0,1,1]
	v_pk_fma_f32 v[86:87], v[98:99], v[22:23], v[86:87] op_sel_hi:[0,1,1]
	v_pk_mul_f32 v[98:99], v[80:81], v[40:41]
	v_pk_mul_f32 v[100:101], v[80:81], v[32:33]
	v_pk_fma_f32 v[98:99], v[82:83], v[42:43], v[98:99]
	v_pk_fma_f32 v[100:101], v[82:83], v[34:35], v[100:101]
	v_pk_fma_f32 v[98:99], v[84:85], v[44:45], v[98:99]
	v_pk_fma_f32 v[100:101], v[84:85], v[36:37], v[100:101]
	v_pk_fma_f32 v[98:99], v[86:87], v[46:47], v[98:99]
	v_pk_fma_f32 v[100:101], v[86:87], v[38:39], v[100:101]
	v_add_f32_e32 v98, v98, v99
	v_add_f32_e32 v100, v100, v101
	ds_read_b128 v[0:3], v97 offset:12288
	ds_read_b128 v[4:7], v97 offset:12304
	v_add_f32_dpp v98, v98, v98 quad_perm:[1,0,3,2] row_mask:0xf bank_mask:0xf bound_ctrl:1
	v_add_f32_dpp v100, v100, v100 quad_perm:[1,0,3,2] row_mask:0xf bank_mask:0xf bound_ctrl:1
	ds_read_b128 v[8:11], v97 offset:12544
	ds_read_b128 v[12:15], v97 offset:12560
	v_add_f32_dpp v98, v98, v98 quad_perm:[2,3,0,1] row_mask:0xf bank_mask:0xf bound_ctrl:1
	v_add_f32_dpp v100, v100, v100 quad_perm:[2,3,0,1] row_mask:0xf bank_mask:0xf bound_ctrl:1
	ds_read_b128 v[24:27], v97 offset:13056
	ds_read_b128 v[28:31], v97 offset:13072
	v_add_f32_dpp v98, v98, v98 row_half_mirror row_mask:0xf bank_mask:0xf bound_ctrl:1
	v_add_f32_dpp v100, v100, v100 row_half_mirror row_mask:0xf bank_mask:0xf bound_ctrl:1
	ds_read_b32 v88, v102 offset:13568
	ds_read_b128 v[16:19], v97 offset:12800
	ds_read_b128 v[20:23], v97 offset:12816
	ds_read_b128 v[32:35], v97 offset:13312
	ds_read_b128 v[36:39], v97 offset:13328
	ds_write_b32 v89, v100 offset:768
	s_waitcnt lgkmcnt(9)
	v_pk_mul_f32 v[80:81], v[80:81], v[48:49]
	v_pk_mul_f32 v[82:83], v[82:83], v[50:51]
	v_pk_mul_f32 v[84:85], v[84:85], v[52:53]
	v_pk_mul_f32 v[86:87], v[86:87], v[54:55]
	v_pk_fma_f32 v[80:81], v[90:91], v[64:65], v[80:81] op_sel_hi:[0,1,1]
	v_pk_fma_f32 v[82:83], v[90:91], v[66:67], v[82:83] op_sel_hi:[0,1,1]
	v_pk_fma_f32 v[84:85], v[90:91], v[68:69], v[84:85] op_sel_hi:[0,1,1]
	v_pk_fma_f32 v[86:87], v[90:91], v[70:71], v[86:87] op_sel_hi:[0,1,1]
	v_pk_fma_f32 v[80:81], v[98:99], v[56:57], v[80:81] op_sel_hi:[0,1,1]
	v_pk_fma_f32 v[82:83], v[98:99], v[58:59], v[82:83] op_sel_hi:[0,1,1]
	v_pk_fma_f32 v[84:85], v[98:99], v[60:61], v[84:85] op_sel_hi:[0,1,1]
	v_pk_fma_f32 v[86:87], v[98:99], v[62:63], v[86:87] op_sel_hi:[0,1,1]
	v_pk_mul_f32 v[98:99], v[80:81], v[0:1]
	v_pk_mul_f32 v[100:101], v[80:81], v[72:73]
	v_pk_fma_f32 v[98:99], v[82:83], v[2:3], v[98:99]
	v_pk_fma_f32 v[100:101], v[82:83], v[74:75], v[100:101]
	v_pk_fma_f32 v[98:99], v[84:85], v[4:5], v[98:99]
	v_pk_fma_f32 v[100:101], v[84:85], v[76:77], v[100:101]
	v_pk_fma_f32 v[98:99], v[86:87], v[6:7], v[98:99]
	v_pk_fma_f32 v[100:101], v[86:87], v[78:79], v[100:101]
	v_add_f32_e32 v98, v98, v99
	v_add_f32_e32 v100, v100, v101
	ds_read_b128 v[40:43], v97 offset:13824
	ds_read_b128 v[44:47], v97 offset:13840
	v_add_f32_dpp v98, v98, v98 quad_perm:[1,0,3,2] row_mask:0xf bank_mask:0xf bound_ctrl:1
	v_add_f32_dpp v100, v100, v100 quad_perm:[1,0,3,2] row_mask:0xf bank_mask:0xf bound_ctrl:1
	ds_read_b128 v[48:51], v97 offset:14080
	ds_read_b128 v[52:55], v97 offset:14096
	v_add_f32_dpp v98, v98, v98 quad_perm:[2,3,0,1] row_mask:0xf bank_mask:0xf bound_ctrl:1
	v_add_f32_dpp v100, v100, v100 quad_perm:[2,3,0,1] row_mask:0xf bank_mask:0xf bound_ctrl:1
	ds_read_b128 v[64:67], v97 offset:14592
	ds_read_b128 v[68:71], v97 offset:14608
	v_add_f32_dpp v98, v98, v98 row_half_mirror row_mask:0xf bank_mask:0xf bound_ctrl:1
	v_add_f32_dpp v100, v100, v100 row_half_mirror row_mask:0xf bank_mask:0xf bound_ctrl:1
	ds_read_b32 v90, v102 offset:15104
	ds_read_b128 v[56:59], v97 offset:14336
	ds_read_b128 v[60:63], v97 offset:14352
	ds_read_b128 v[72:75], v97 offset:14848
	ds_read_b128 v[76:79], v97 offset:14864
	ds_write_b32 v89, v100 offset:896
	s_add_i32 s7, s7, -8
	v_add_u32_e32 v97, 0x3000, v97
	v_add_u32_e32 v102, 0x3000, v102
	v_add_u32_e32 v89, 0x400, v89
	s_cmp_eq_u32 s7, 0
	s_cbranch_scc0 .Lscnh_loop
	s_branch .LBB0_469
